# on top of best: s_setprio 0 after the block-closing barrier instead of before it
# speedup vs baseline: 1.0027x; 1.0027x over previous
; #define PG8_STAGE(bufoff, gbase, voff) do { _Pragma("unroll") for (int _i = 0; _i < 2; ++_i) \
;         __builtin_amdgcn_global_load_lds((const unsigned*)((const char*)(gbase) + (voff)[_i]), (PG8_LAS unsigned*)(lds + (bufoff) + ldsw + _i * 8192), 16, 0, 0); } while (0)
; #define PG8_LDA(dst, b, h) do { _Pragma("unroll") for (int m = 0; m < 4; ++m) _Pragma("unroll") for (int k = 0; k < 2; ++k) dst[m][k] = *(const PG8_LAS bf16x8*)(lds + PG8_SA(b, h) + aoff + m * 2048 + k * 1024); } while (0)
; #define PG8_LDB(dst, b, h) do { _Pragma("unroll") for (int n = 0; n < 2; ++n) _Pragma("unroll") for (int k = 0; k < 2; ++k) dst[n][k] = *(const PG8_LAS bf16x8*)(lds + PG8_SB(b, h) + boff + n * 2048 + k * 1024); } while (0)
; #define PG8_MMA(ai, bj, At, Bt) do { __builtin_amdgcn_s_setprio(1); _Pragma("unroll") for (int m = 0; m < 4; ++m) _Pragma("unroll") for (int n = 0; n < 2; ++n) _Pragma("unroll") for (int k = 0; k < 2; ++k) \
;         acc[ai][bj][m][n] = __builtin_amdgcn_mfma_f32_16x16x32_bf16(Bt[n][k], At[m][k], acc[ai][bj][m][n], 0, 0, 0); __builtin_amdgcn_s_setprio(0); } while (0)
; #define PG8_WAIT_V(n) asm volatile("s_waitcnt vmcnt(" #n ")" ::: "memory")
; #define PG8_WAIT_L(n) asm volatile("s_waitcnt lgkmcnt(" #n ")" ::: "memory")
; #define PG8_BAR __builtin_amdgcn_s_barrier()
; #define PG8_SCHED __builtin_amdgcn_sched_barrier(0)
; template <class Epi, class Sched, bool ALIGN_EPI = false, bool SP2 = false>
; __device__ __forceinline__ void gemm_phase(PG8_LAS unsigned char* lds, const Gemm g, const Sched& S, const Epi& E) {
;     ...
;             PG8_LDB(B0, 0, 0); PG8_LDB(B1, 0, 1); PG8_SCHED; PG8_LDA(At, 0, 0); PG8_STAGE(PG8_SA(1, 1), a1 + hstep, voffA);
;             PG8_WAIT_V(8); PG8_WAIT_L(0); PG8_BAR; PG8_MMA(0, 0, At, B0); PG8_MMA(0, 1, At, B1); PG8_BAR; PG8_SCHED;
;             PG8_LDA(At, 0, 1); PG8_STAGE(PG8_SB(0, 0), b2, voffB); PG8_STAGE(PG8_SB(0, 1), b2 + hstep, voffB); PG8_STAGE(PG8_SA(0, 0), a2, voffA);
;             PG8_WAIT_V(8); PG8_WAIT_L(0); PG8_BAR; PG8_MMA(1, 0, At, B0); PG8_MMA(1, 1, At, B1); PG8_BAR; PG8_SCHED;
.LBB0_132:
	s_add_u32 s18, s46, 0xfffc0080
	s_addc_u32 s38, s47, -1
	s_add_i32 s39, 0, 0x10000
	s_cmp_eq_u32 s85, 12
	s_cselect_b32 s81, s33, s38
	s_cselect_b32 s80, s73, s18
	v_add_u32_e32 v0, s39, v176
	s_cselect_b32 s45, s75, s84
	s_cselect_b32 s44, s82, s83
	s_add_i32 s18, 0, 0x14000
	ds_read_b128 v[144:147], v0
	ds_read_b128 v[148:151], v0 offset:1024
	ds_read_b128 v[152:155], v0 offset:2048
	ds_read_b128 v[156:159], v0 offset:3072
	v_add_u32_e32 v0, s18, v176
	ds_read_b128 v[160:163], v0
	ds_read_b128 v[164:167], v0 offset:1024
	ds_read_b128 v[168:171], v0 offset:2048
	ds_read_b128 v[172:175], v0 offset:3072
	v_lshl_add_u64 v[218:219], s[46:47], 0, v[140:141]
	s_add_i32 m0, s92, 0xc000
	ds_read_b128 v[180:183], v178
	ds_read_b128 v[184:187], v178 offset:1024
	ds_read_b128 v[188:191], v178 offset:2048
	ds_read_b128 v[192:195], v178 offset:3072
	ds_read_b128 v[202:205], v178 offset:4096
	ds_read_b128 v[206:209], v178 offset:5120
	ds_read_b128 v[210:213], v178 offset:6144
	ds_read_b128 v[214:217], v178 offset:7168
	global_load_lds_dwordx4 v[218:219], off
	v_lshl_add_u64 v[218:219], s[46:47], 0, v[142:143]
	s_add_i32 m0, s92, 0xe000
	s_nop 0
	global_load_lds_dwordx4 v[218:219], off
	s_waitcnt vmcnt(8)
	s_waitcnt lgkmcnt(0)
	s_barrier
	s_setprio 1
	v_mfma_f32_16x16x32_bf16 v[118:121], v[144:147], v[180:183], v[118:121]
	v_mfma_f32_16x16x32_bf16 v[118:121], v[148:151], v[184:187], v[118:121]
	v_mfma_f32_16x16x32_bf16 v[102:105], v[144:147], v[188:191], v[102:105]
	v_mfma_f32_16x16x32_bf16 v[102:105], v[148:151], v[192:195], v[102:105]
	v_mfma_f32_16x16x32_bf16 v[86:89], v[144:147], v[202:205], v[86:89]
	v_mfma_f32_16x16x32_bf16 v[86:89], v[148:151], v[206:209], v[86:89]
	v_mfma_f32_16x16x32_bf16 v[70:73], v[144:147], v[210:213], v[70:73]
	v_mfma_f32_16x16x32_bf16 v[70:73], v[148:151], v[214:217], v[70:73]
	v_mfma_f32_16x16x32_bf16 v[114:117], v[152:155], v[180:183], v[114:117]
	v_mfma_f32_16x16x32_bf16 v[114:117], v[156:159], v[184:187], v[114:117]
	v_mfma_f32_16x16x32_bf16 v[98:101], v[152:155], v[188:191], v[98:101]
	v_mfma_f32_16x16x32_bf16 v[98:101], v[156:159], v[192:195], v[98:101]
	v_mfma_f32_16x16x32_bf16 v[82:85], v[152:155], v[202:205], v[82:85]
	v_mfma_f32_16x16x32_bf16 v[82:85], v[156:159], v[206:209], v[82:85]
	v_mfma_f32_16x16x32_bf16 v[66:69], v[152:155], v[210:213], v[66:69]
	v_mfma_f32_16x16x32_bf16 v[66:69], v[156:159], v[214:217], v[66:69]
	v_mfma_f32_16x16x32_bf16 v[126:129], v[160:163], v[180:183], v[126:129]
	v_mfma_f32_16x16x32_bf16 v[126:129], v[164:167], v[184:187], v[126:129]
	v_mfma_f32_16x16x32_bf16 v[110:113], v[160:163], v[188:191], v[110:113]
	v_mfma_f32_16x16x32_bf16 v[110:113], v[164:167], v[192:195], v[110:113]
	v_mfma_f32_16x16x32_bf16 v[94:97], v[160:163], v[202:205], v[94:97]
	v_mfma_f32_16x16x32_bf16 v[94:97], v[164:167], v[206:209], v[94:97]
	v_mfma_f32_16x16x32_bf16 v[78:81], v[160:163], v[210:213], v[78:81]
	v_mfma_f32_16x16x32_bf16 v[78:81], v[164:167], v[214:217], v[78:81]
	v_mfma_f32_16x16x32_bf16 v[122:125], v[168:171], v[180:183], v[122:125]
	v_mfma_f32_16x16x32_bf16 v[122:125], v[172:175], v[184:187], v[122:125]
	v_mfma_f32_16x16x32_bf16 v[106:109], v[168:171], v[188:191], v[106:109]
	v_mfma_f32_16x16x32_bf16 v[106:109], v[172:175], v[192:195], v[106:109]
	v_mfma_f32_16x16x32_bf16 v[90:93], v[168:171], v[202:205], v[90:93]
	v_mfma_f32_16x16x32_bf16 v[90:93], v[172:175], v[206:209], v[90:93]
	v_mfma_f32_16x16x32_bf16 v[74:77], v[168:171], v[210:213], v[74:77]
	v_mfma_f32_16x16x32_bf16 v[74:77], v[172:175], v[214:217], v[74:77]
	s_barrier
	s_setprio 0
	s_add_i32 s38, s39, s91
	v_lshl_add_u64 v[218:219], s[44:45], 0, v[134:135]
	s_mov_b32 m0, s38
	ds_read_b128 v[180:183], v178 offset:16384
	ds_read_b128 v[184:187], v178 offset:17408
	ds_read_b128 v[188:191], v178 offset:18432
	ds_read_b128 v[192:195], v178 offset:19456
	ds_read_b128 v[202:205], v178 offset:20480
	ds_read_b128 v[206:209], v178 offset:21504
	ds_read_b128 v[210:213], v178 offset:22528
	ds_read_b128 v[214:217], v178 offset:23552
	global_load_lds_dwordx4 v[218:219], off
	s_add_i32 m0, s38, 0x2000
	s_add_u32 s38, s44, 0x40000
	v_lshl_add_u64 v[220:221], s[44:45], 0, v[130:131]
	s_addc_u32 s39, s45, 0
	s_add_i32 s18, s18, s91
	global_load_lds_dwordx4 v[220:221], off
	v_lshl_add_u64 v[222:223], s[38:39], 0, v[134:135]
	s_mov_b32 m0, s18
	v_lshl_add_u64 v[224:225], s[80:81], 0, v[132:133]
	global_load_lds_dwordx4 v[222:223], off
	v_lshl_add_u64 v[222:223], s[38:39], 0, v[130:131]
	s_add_i32 m0, s18, 0x2000
	s_nop 0
	global_load_lds_dwordx4 v[222:223], off
	v_lshl_add_u64 v[222:223], s[80:81], 0, v[136:137]
	s_mov_b32 m0, s92
	s_nop 0
	global_load_lds_dwordx4 v[222:223], off
	s_mov_b32 m0, s93
	s_nop 0
	global_load_lds_dwordx4 v[224:225], off
	s_waitcnt vmcnt(8)
	s_waitcnt lgkmcnt(0)
	s_barrier
; #define PG8_STAGE(bufoff, gbase, voff) do { _Pragma("unroll") for (int _i = 0; _i < 2; ++_i) \
;         __builtin_amdgcn_global_load_lds((const unsigned*)((const char*)(gbase) + (voff)[_i]), (PG8_LAS unsigned*)(lds + (bufoff) + ldsw + _i * 8192), 16, 0, 0); } while (0)
; #define PG8_LDA(dst, b, h) do { _Pragma("unroll") for (int m = 0; m < 4; ++m) _Pragma("unroll") for (int k = 0; k < 2; ++k) dst[m][k] = *(const PG8_LAS bf16x8*)(lds + PG8_SA(b, h) + aoff + m * 2048 + k * 1024); } while (0)
; #define PG8_LDB(dst, b, h) do { _Pragma("unroll") for (int n = 0; n < 2; ++n) _Pragma("unroll") for (int k = 0; k < 2; ++k) dst[n][k] = *(const PG8_LAS bf16x8*)(lds + PG8_SB(b, h) + boff + n * 2048 + k * 1024); } while (0)
; #define PG8_MMA(ai, bj, At, Bt) do { __builtin_amdgcn_s_setprio(1); _Pragma("unroll") for (int m = 0; m < 4; ++m) _Pragma("unroll") for (int n = 0; n < 2; ++n) _Pragma("unroll") for (int k = 0; k < 2; ++k) \
;         acc[ai][bj][m][n] = __builtin_amdgcn_mfma_f32_16x16x32_bf16(Bt[n][k], At[m][k], acc[ai][bj][m][n], 0, 0, 0); __builtin_amdgcn_s_setprio(0); } while (0)
; #define PG8_WAIT_V(n) asm volatile("s_waitcnt vmcnt(" #n ")" ::: "memory")
; #define PG8_WAIT_L(n) asm volatile("s_waitcnt lgkmcnt(" #n ")" ::: "memory")
; #define PG8_BAR __builtin_amdgcn_s_barrier()
; #define PG8_SCHED __builtin_amdgcn_sched_barrier(0)
; template <class Epi, class Sched, bool ALIGN_EPI = false, bool SP2 = false>
; __device__ __forceinline__ void gemm_phase(PG8_LAS unsigned char* lds, const Gemm g, const Sched& S, const Epi& E) {
;     ...
;             PG8_WAIT_V(8); PG8_WAIT_L(0); PG8_BAR; PG8_MMA(1, 0, At, B0); PG8_MMA(1, 1, At, B1); PG8_BAR; PG8_SCHED;
;             PG8_LDB(B0, 1, 0); PG8_LDB(B1, 1, 1); PG8_SCHED; PG8_LDA(At, 1, 0); PG8_STAGE(PG8_SA(0, 1), a2 + hstep, voffA);
;             PG8_WAIT_V(8); PG8_WAIT_L(0); PG8_BAR; PG8_MMA(0, 0, At, B0); PG8_MMA(0, 1, At, B1); PG8_BAR; PG8_SCHED;
	s_setprio 1
	v_mfma_f32_16x16x32_bf16 v[54:57], v[144:147], v[180:183], v[54:57]
	v_mfma_f32_16x16x32_bf16 v[54:57], v[148:151], v[184:187], v[54:57]
	v_mfma_f32_16x16x32_bf16 v[38:41], v[144:147], v[188:191], v[38:41]
	v_mfma_f32_16x16x32_bf16 v[38:41], v[148:151], v[192:195], v[38:41]
	v_mfma_f32_16x16x32_bf16 v[22:25], v[144:147], v[202:205], v[22:25]
	v_mfma_f32_16x16x32_bf16 v[22:25], v[148:151], v[206:209], v[22:25]
	v_mfma_f32_16x16x32_bf16 v[6:9], v[144:147], v[210:213], v[6:9]
	v_mfma_f32_16x16x32_bf16 v[6:9], v[148:151], v[214:217], v[6:9]
	v_mfma_f32_16x16x32_bf16 v[50:53], v[152:155], v[180:183], v[50:53]
	v_mfma_f32_16x16x32_bf16 v[50:53], v[156:159], v[184:187], v[50:53]
	v_mfma_f32_16x16x32_bf16 v[34:37], v[152:155], v[188:191], v[34:37]
	v_mfma_f32_16x16x32_bf16 v[34:37], v[156:159], v[192:195], v[34:37]
	v_mfma_f32_16x16x32_bf16 v[18:21], v[152:155], v[202:205], v[18:21]
	v_mfma_f32_16x16x32_bf16 v[18:21], v[156:159], v[206:209], v[18:21]
	v_mfma_f32_16x16x32_bf16 v[2:5], v[152:155], v[210:213], v[2:5]
	v_mfma_f32_16x16x32_bf16 v[2:5], v[156:159], v[214:217], v[2:5]
	v_mfma_f32_16x16x32_bf16 v[62:65], v[160:163], v[180:183], v[62:65]
	v_mfma_f32_16x16x32_bf16 v[62:65], v[164:167], v[184:187], v[62:65]
	v_mfma_f32_16x16x32_bf16 v[46:49], v[160:163], v[188:191], v[46:49]
	v_mfma_f32_16x16x32_bf16 v[46:49], v[164:167], v[192:195], v[46:49]
	v_mfma_f32_16x16x32_bf16 v[30:33], v[160:163], v[202:205], v[30:33]
	v_mfma_f32_16x16x32_bf16 v[30:33], v[164:167], v[206:209], v[30:33]
	v_mfma_f32_16x16x32_bf16 v[10:13], v[160:163], v[210:213], v[10:13]
	v_mfma_f32_16x16x32_bf16 v[10:13], v[164:167], v[214:217], v[10:13]
	v_mfma_f32_16x16x32_bf16 v[58:61], v[168:171], v[180:183], v[58:61]
	v_mfma_f32_16x16x32_bf16 v[58:61], v[172:175], v[184:187], v[58:61]
	v_mfma_f32_16x16x32_bf16 v[42:45], v[168:171], v[188:191], v[42:45]
	v_mfma_f32_16x16x32_bf16 v[42:45], v[172:175], v[192:195], v[42:45]
	v_mfma_f32_16x16x32_bf16 v[26:29], v[168:171], v[202:205], v[26:29]
	v_mfma_f32_16x16x32_bf16 v[26:29], v[172:175], v[206:209], v[26:29]
	v_mfma_f32_16x16x32_bf16 v[14:17], v[168:171], v[210:213], v[14:17]
	v_mfma_f32_16x16x32_bf16 v[14:17], v[172:175], v[214:217], v[14:17]
	s_barrier
	s_setprio 0
	s_add_i32 s18, 0, 0x18000
	v_add_u32_e32 v0, s18, v176
	s_add_i32 vcc_lo, 0, 0x1c000
	ds_read_b128 v[144:147], v0
	ds_read_b128 v[148:151], v0 offset:1024
	ds_read_b128 v[152:155], v0 offset:2048
	ds_read_b128 v[156:159], v0 offset:3072
	v_add_u32_e32 v0, vcc_lo, v176
	ds_read_b128 v[160:163], v0
	ds_read_b128 v[164:167], v0 offset:1024
	ds_read_b128 v[168:171], v0 offset:2048
	ds_read_b128 v[172:175], v0 offset:3072
	s_add_u32 s38, s80, 0x40000
	s_addc_u32 s39, s81, 0
	s_mov_b32 m0, s94
	v_lshl_add_u64 v[226:227], s[38:39], 0, v[136:137]
	ds_read_b128 v[180:183], v178 offset:32768
	ds_read_b128 v[184:187], v178 offset:33792
	ds_read_b128 v[188:191], v178 offset:34816
	ds_read_b128 v[192:195], v178 offset:35840
	ds_read_b128 v[202:205], v178 offset:36864
	ds_read_b128 v[206:209], v178 offset:37888
	ds_read_b128 v[210:213], v178 offset:38912
	ds_read_b128 v[214:217], v178 offset:39936
	global_load_lds_dwordx4 v[226:227], off
	v_lshl_add_u64 v[226:227], s[38:39], 0, v[132:133]
	s_mov_b32 m0, s95
	s_nop 0
	global_load_lds_dwordx4 v[226:227], off
	s_waitcnt vmcnt(8)
	s_waitcnt lgkmcnt(0)
	s_barrier
	s_setprio 1
	v_mfma_f32_16x16x32_bf16 v[118:121], v[144:147], v[180:183], v[118:121]
	v_mfma_f32_16x16x32_bf16 v[118:121], v[148:151], v[184:187], v[118:121]
	v_mfma_f32_16x16x32_bf16 v[102:105], v[144:147], v[188:191], v[102:105]
	v_mfma_f32_16x16x32_bf16 v[102:105], v[148:151], v[192:195], v[102:105]
	v_mfma_f32_16x16x32_bf16 v[86:89], v[144:147], v[202:205], v[86:89]
	v_mfma_f32_16x16x32_bf16 v[86:89], v[148:151], v[206:209], v[86:89]
	v_mfma_f32_16x16x32_bf16 v[70:73], v[144:147], v[210:213], v[70:73]
	v_mfma_f32_16x16x32_bf16 v[70:73], v[148:151], v[214:217], v[70:73]
	v_mfma_f32_16x16x32_bf16 v[114:117], v[152:155], v[180:183], v[114:117]
	v_mfma_f32_16x16x32_bf16 v[114:117], v[156:159], v[184:187], v[114:117]
	v_mfma_f32_16x16x32_bf16 v[98:101], v[152:155], v[188:191], v[98:101]
	v_mfma_f32_16x16x32_bf16 v[98:101], v[156:159], v[192:195], v[98:101]
	v_mfma_f32_16x16x32_bf16 v[82:85], v[152:155], v[202:205], v[82:85]
	v_mfma_f32_16x16x32_bf16 v[82:85], v[156:159], v[206:209], v[82:85]
	v_mfma_f32_16x16x32_bf16 v[66:69], v[152:155], v[210:213], v[66:69]
	v_mfma_f32_16x16x32_bf16 v[66:69], v[156:159], v[214:217], v[66:69]
	v_mfma_f32_16x16x32_bf16 v[126:129], v[160:163], v[180:183], v[126:129]
	v_mfma_f32_16x16x32_bf16 v[126:129], v[164:167], v[184:187], v[126:129]
	v_mfma_f32_16x16x32_bf16 v[110:113], v[160:163], v[188:191], v[110:113]
	v_mfma_f32_16x16x32_bf16 v[110:113], v[164:167], v[192:195], v[110:113]
	v_mfma_f32_16x16x32_bf16 v[94:97], v[160:163], v[202:205], v[94:97]
	v_mfma_f32_16x16x32_bf16 v[94:97], v[164:167], v[206:209], v[94:97]
	v_mfma_f32_16x16x32_bf16 v[78:81], v[160:163], v[210:213], v[78:81]
	v_mfma_f32_16x16x32_bf16 v[78:81], v[164:167], v[214:217], v[78:81]
	v_mfma_f32_16x16x32_bf16 v[122:125], v[168:171], v[180:183], v[122:125]
	v_mfma_f32_16x16x32_bf16 v[122:125], v[172:175], v[184:187], v[122:125]
	v_mfma_f32_16x16x32_bf16 v[106:109], v[168:171], v[188:191], v[106:109]
	v_mfma_f32_16x16x32_bf16 v[106:109], v[172:175], v[192:195], v[106:109]
	v_mfma_f32_16x16x32_bf16 v[90:93], v[168:171], v[202:205], v[90:93]
	v_mfma_f32_16x16x32_bf16 v[90:93], v[172:175], v[206:209], v[90:93]
	v_mfma_f32_16x16x32_bf16 v[74:77], v[168:171], v[210:213], v[74:77]
	v_mfma_f32_16x16x32_bf16 v[74:77], v[172:175], v[214:217], v[74:77]
	s_barrier
; #define PG8_STAGE(bufoff, gbase, voff) do { _Pragma("unroll") for (int _i = 0; _i < 2; ++_i) \
;         __builtin_amdgcn_global_load_lds((const unsigned*)((const char*)(gbase) + (voff)[_i]), (PG8_LAS unsigned*)(lds + (bufoff) + ldsw + _i * 8192), 16, 0, 0); } while (0)
; #define PG8_LDA(dst, b, h) do { _Pragma("unroll") for (int m = 0; m < 4; ++m) _Pragma("unroll") for (int k = 0; k < 2; ++k) dst[m][k] = *(const PG8_LAS bf16x8*)(lds + PG8_SA(b, h) + aoff + m * 2048 + k * 1024); } while (0)
; #define PG8_MMA(ai, bj, At, Bt) do { __builtin_amdgcn_s_setprio(1); _Pragma("unroll") for (int m = 0; m < 4; ++m) _Pragma("unroll") for (int n = 0; n < 2; ++n) _Pragma("unroll") for (int k = 0; k < 2; ++k) \
;         acc[ai][bj][m][n] = __builtin_amdgcn_mfma_f32_16x16x32_bf16(Bt[n][k], At[m][k], acc[ai][bj][m][n], 0, 0, 0); __builtin_amdgcn_s_setprio(0); } while (0)
; #define PG8_WAIT_V(n) asm volatile("s_waitcnt vmcnt(" #n ")" ::: "memory")
; #define PG8_WAIT_L(n) asm volatile("s_waitcnt lgkmcnt(" #n ")" ::: "memory")
; #define PG8_BAR __builtin_amdgcn_s_barrier()
; #define PG8_SCHED __builtin_amdgcn_sched_barrier(0)
; template <class Epi, class Sched, bool ALIGN_EPI = false, bool SP2 = false>
; __device__ __forceinline__ void gemm_phase(PG8_LAS unsigned char* lds, const Gemm g, const Sched& S, const Epi& E) {
;     ...
;         for (int t = 0; t < nt; t += 2) {
;             const bool last = (t == nt - 2);
;     ...
;             PG8_LDA(At, 1, 1); PG8_STAGE(PG8_SB(1, 0), b3, voffB); PG8_STAGE(PG8_SB(1, 1), b3 + hstep, voffB); PG8_STAGE(PG8_SA(1, 0), a3, voffA);
;             PG8_WAIT_V(8); PG8_WAIT_L(0); PG8_BAR; PG8_MMA(1, 0, At, B0); PG8_MMA(1, 1, At, B1); PG8_BAR; PG8_SCHED;
	s_setprio 0
	s_add_i32 s18, s18, s91
	v_lshl_add_u64 v[218:219], v[218:219], 0, s[30:31]
	s_mov_b32 m0, s18
	ds_read_b128 v[180:183], v178 offset:49152
	ds_read_b128 v[184:187], v178 offset:50176
	ds_read_b128 v[188:191], v178 offset:51200
	ds_read_b128 v[192:195], v178 offset:52224
	ds_read_b128 v[202:205], v178 offset:53248
	ds_read_b128 v[206:209], v178 offset:54272
	ds_read_b128 v[210:213], v178 offset:55296
	ds_read_b128 v[214:217], v178 offset:56320
	global_load_lds_dwordx4 v[218:219], off
	s_add_i32 m0, s18, 0x2000
	s_add_u32 s38, s44, 0x40080
	v_lshl_add_u64 v[218:219], v[220:221], 0, s[30:31]
	s_addc_u32 s39, s45, 0
	s_add_i32 s18, vcc_lo, s91
	global_load_lds_dwordx4 v[218:219], off
	v_lshl_add_u64 v[218:219], s[38:39], 0, v[134:135]
	s_mov_b32 m0, s18
	s_nop 0
	global_load_lds_dwordx4 v[218:219], off
	v_lshl_add_u64 v[218:219], s[38:39], 0, v[130:131]
	s_add_i32 m0, s18, 0x2000
	s_nop 0
	global_load_lds_dwordx4 v[218:219], off
	v_lshl_add_u64 v[218:219], v[222:223], 0, s[30:31]
	s_mov_b32 m0, s7
	s_nop 0
	global_load_lds_dwordx4 v[218:219], off
	v_lshl_add_u64 v[218:219], v[224:225], 0, s[30:31]
	s_mov_b32 m0, s96
	s_nop 0
	global_load_lds_dwordx4 v[218:219], off
	s_waitcnt vmcnt(8)
	s_waitcnt lgkmcnt(0)
	s_barrier
	s_setprio 1
	v_mfma_f32_16x16x32_bf16 v[54:57], v[144:147], v[180:183], v[54:57]
	v_mfma_f32_16x16x32_bf16 v[54:57], v[148:151], v[184:187], v[54:57]
	v_mfma_f32_16x16x32_bf16 v[38:41], v[144:147], v[188:191], v[38:41]
	v_mfma_f32_16x16x32_bf16 v[38:41], v[148:151], v[192:195], v[38:41]
	v_mfma_f32_16x16x32_bf16 v[22:25], v[144:147], v[202:205], v[22:25]
	v_mfma_f32_16x16x32_bf16 v[22:25], v[148:151], v[206:209], v[22:25]
	v_mfma_f32_16x16x32_bf16 v[6:9], v[144:147], v[210:213], v[6:9]
	v_mfma_f32_16x16x32_bf16 v[6:9], v[148:151], v[214:217], v[6:9]
	v_mfma_f32_16x16x32_bf16 v[50:53], v[152:155], v[180:183], v[50:53]
	v_mfma_f32_16x16x32_bf16 v[50:53], v[156:159], v[184:187], v[50:53]
	v_mfma_f32_16x16x32_bf16 v[34:37], v[152:155], v[188:191], v[34:37]
	v_mfma_f32_16x16x32_bf16 v[34:37], v[156:159], v[192:195], v[34:37]
	v_mfma_f32_16x16x32_bf16 v[18:21], v[152:155], v[202:205], v[18:21]
	v_mfma_f32_16x16x32_bf16 v[18:21], v[156:159], v[206:209], v[18:21]
	v_mfma_f32_16x16x32_bf16 v[2:5], v[152:155], v[210:213], v[2:5]
	v_mfma_f32_16x16x32_bf16 v[2:5], v[156:159], v[214:217], v[2:5]
	v_mfma_f32_16x16x32_bf16 v[62:65], v[160:163], v[180:183], v[62:65]
	v_mfma_f32_16x16x32_bf16 v[62:65], v[164:167], v[184:187], v[62:65]
	v_mfma_f32_16x16x32_bf16 v[46:49], v[160:163], v[188:191], v[46:49]
	v_mfma_f32_16x16x32_bf16 v[46:49], v[164:167], v[192:195], v[46:49]
	v_mfma_f32_16x16x32_bf16 v[30:33], v[160:163], v[202:205], v[30:33]
	v_mfma_f32_16x16x32_bf16 v[30:33], v[164:167], v[206:209], v[30:33]
	v_mfma_f32_16x16x32_bf16 v[10:13], v[160:163], v[210:213], v[10:13]
	v_mfma_f32_16x16x32_bf16 v[10:13], v[164:167], v[214:217], v[10:13]
	v_mfma_f32_16x16x32_bf16 v[58:61], v[168:171], v[180:183], v[58:61]
	v_mfma_f32_16x16x32_bf16 v[58:61], v[172:175], v[184:187], v[58:61]
	v_mfma_f32_16x16x32_bf16 v[42:45], v[168:171], v[188:191], v[42:45]
	v_mfma_f32_16x16x32_bf16 v[42:45], v[172:175], v[192:195], v[42:45]
	v_mfma_f32_16x16x32_bf16 v[26:29], v[168:171], v[202:205], v[26:29]
	v_mfma_f32_16x16x32_bf16 v[26:29], v[172:175], v[206:209], v[26:29]
	v_mfma_f32_16x16x32_bf16 v[14:17], v[168:171], v[210:213], v[14:17]
	v_mfma_f32_16x16x32_bf16 v[14:17], v[172:175], v[214:217], v[14:17]
	s_barrier
	s_setprio 0
	s_add_i32 s85, s85, 2
	s_add_u32 s46, s46, 0x100
	s_addc_u32 s47, s47, 0
	s_add_u32 s83, s83, 0x100
	s_addc_u32 s84, s84, 0
	s_cmp_gt_u32 s85, 13
	s_cbranch_scc0 .LBB0_132
	s_and_b64 vcc, exec, s[10:11]
	s_cbranch_vccz .LBB0_135
	s_barrier

; #define PG8_STAGE(bufoff, gbase, voff) do { _Pragma("unroll") for (int _i = 0; _i < 2; ++_i) \
;         __builtin_amdgcn_global_load_lds((const unsigned*)((const char*)(gbase) + (voff)[_i]), (PG8_LAS unsigned*)(lds + (bufoff) + ldsw + _i * 8192), 16, 0, 0); } while (0)
; #define PG8_LDA(dst, b, h) do { _Pragma("unroll") for (int m = 0; m < 4; ++m) _Pragma("unroll") for (int k = 0; k < 2; ++k) dst[m][k] = *(const PG8_LAS bf16x8*)(lds + PG8_SA(b, h) + aoff + m * 2048 + k * 1024); } while (0)
; #define PG8_LDB(dst, b, h) do { _Pragma("unroll") for (int n = 0; n < 2; ++n) _Pragma("unroll") for (int k = 0; k < 2; ++k) dst[n][k] = *(const PG8_LAS bf16x8*)(lds + PG8_SB(b, h) + boff + n * 2048 + k * 1024); } while (0)
; #define PG8_MMA(ai, bj, At, Bt) do { __builtin_amdgcn_s_setprio(1); _Pragma("unroll") for (int m = 0; m < 4; ++m) _Pragma("unroll") for (int n = 0; n < 2; ++n) _Pragma("unroll") for (int k = 0; k < 2; ++k) \
;         acc[ai][bj][m][n] = __builtin_amdgcn_mfma_f32_16x16x32_bf16(Bt[n][k], At[m][k], acc[ai][bj][m][n], 0, 0, 0); __builtin_amdgcn_s_setprio(0); } while (0)
; #define PG8_WAIT_V(n) asm volatile("s_waitcnt vmcnt(" #n ")" ::: "memory")
; #define PG8_WAIT_L(n) asm volatile("s_waitcnt lgkmcnt(" #n ")" ::: "memory")
; #define PG8_BAR __builtin_amdgcn_s_barrier()
; #define PG8_SCHED __builtin_amdgcn_sched_barrier(0)
; template <class Epi, class Sched, bool ALIGN_EPI = false, bool SP2 = false>
; __device__ __forceinline__ void gemm_phase(PG8_LAS unsigned char* lds, const Gemm g, const Sched& S, const Epi& E) {
;     ...
;             PG8_LDB(B0, 0, 0); PG8_LDB(B1, 0, 1); PG8_SCHED; PG8_LDA(At, 0, 0); PG8_STAGE(PG8_SA(1, 1), a1 + hstep, voffA);
;             PG8_WAIT_V(8); PG8_WAIT_L(0); PG8_BAR; PG8_MMA(0, 0, At, B0); PG8_MMA(0, 1, At, B1); PG8_BAR; PG8_SCHED;
;             PG8_LDA(At, 0, 1); PG8_STAGE(PG8_SB(0, 0), b2, voffB); PG8_STAGE(PG8_SB(0, 1), b2 + hstep, voffB); PG8_STAGE(PG8_SA(0, 0), a2, voffA);
;             PG8_WAIT_V(8); PG8_WAIT_L(0); PG8_BAR; PG8_MMA(1, 0, At, B0); PG8_MMA(1, 1, At, B1); PG8_BAR; PG8_SCHED;
.LBB0_220:
	s_add_u32 s18, s60, 0xfffc0080
	s_addc_u32 s38, s61, -1
	s_add_i32 s39, 0, 0x10000
	s_cmp_eq_u32 s82, 12
	s_cselect_b32 s65, s47, s38
	s_cselect_b32 s64, s78, s18
	v_add_u32_e32 v145, s39, v141
	s_cselect_b32 s57, s49, s81
	s_cselect_b32 s56, s79, s80
	s_add_i32 s18, 0, 0x14000
	ds_read_b128 v[146:149], v145
	ds_read_b128 v[150:153], v145 offset:1024
	ds_read_b128 v[154:157], v145 offset:2048
	ds_read_b128 v[158:161], v145 offset:3072
	v_add_u32_e32 v145, s18, v141
	ds_read_b128 v[162:165], v145
	ds_read_b128 v[166:169], v145 offset:1024
	ds_read_b128 v[170:173], v145 offset:2048
	ds_read_b128 v[174:177], v145 offset:3072
	v_lshl_add_u64 v[194:195], s[60:61], 0, v[136:137]
	s_add_i32 m0, s29, 0xc000
	ds_read_b128 v[178:181], v144
	ds_read_b128 v[182:185], v144 offset:1024
	ds_read_b128 v[186:189], v144 offset:2048
	ds_read_b128 v[190:193], v144 offset:3072
	ds_read_b128 v[202:205], v144 offset:4096
	ds_read_b128 v[206:209], v144 offset:5120
	ds_read_b128 v[210:213], v144 offset:6144
	ds_read_b128 v[214:217], v144 offset:7168
	global_load_lds_dwordx4 v[194:195], off
	v_lshl_add_u64 v[194:195], s[60:61], 0, v[138:139]
	s_add_i32 m0, s29, 0xe000
	s_nop 0
	global_load_lds_dwordx4 v[194:195], off
	s_waitcnt vmcnt(8)
	s_waitcnt lgkmcnt(0)
	s_barrier
	s_setprio 1
	v_mfma_f32_16x16x32_bf16 v[114:117], v[146:149], v[178:181], v[114:117]
	v_mfma_f32_16x16x32_bf16 v[114:117], v[150:153], v[182:185], v[114:117]
	v_mfma_f32_16x16x32_bf16 v[98:101], v[146:149], v[186:189], v[98:101]
	v_mfma_f32_16x16x32_bf16 v[98:101], v[150:153], v[190:193], v[98:101]
	v_mfma_f32_16x16x32_bf16 v[82:85], v[146:149], v[202:205], v[82:85]
	v_mfma_f32_16x16x32_bf16 v[82:85], v[150:153], v[206:209], v[82:85]
	v_mfma_f32_16x16x32_bf16 v[66:69], v[146:149], v[210:213], v[66:69]
	v_mfma_f32_16x16x32_bf16 v[66:69], v[150:153], v[214:217], v[66:69]
	v_mfma_f32_16x16x32_bf16 v[118:121], v[154:157], v[178:181], v[118:121]
	v_mfma_f32_16x16x32_bf16 v[118:121], v[158:161], v[182:185], v[118:121]
	v_mfma_f32_16x16x32_bf16 v[102:105], v[154:157], v[186:189], v[102:105]
	v_mfma_f32_16x16x32_bf16 v[102:105], v[158:161], v[190:193], v[102:105]
	v_mfma_f32_16x16x32_bf16 v[86:89], v[154:157], v[202:205], v[86:89]
	v_mfma_f32_16x16x32_bf16 v[86:89], v[158:161], v[206:209], v[86:89]
	v_mfma_f32_16x16x32_bf16 v[70:73], v[154:157], v[210:213], v[70:73]
	v_mfma_f32_16x16x32_bf16 v[70:73], v[158:161], v[214:217], v[70:73]
	v_mfma_f32_16x16x32_bf16 v[122:125], v[162:165], v[178:181], v[122:125]
	v_mfma_f32_16x16x32_bf16 v[122:125], v[166:169], v[182:185], v[122:125]
	v_mfma_f32_16x16x32_bf16 v[106:109], v[162:165], v[186:189], v[106:109]
	v_mfma_f32_16x16x32_bf16 v[106:109], v[166:169], v[190:193], v[106:109]
	v_mfma_f32_16x16x32_bf16 v[90:93], v[162:165], v[202:205], v[90:93]
	v_mfma_f32_16x16x32_bf16 v[90:93], v[166:169], v[206:209], v[90:93]
	v_mfma_f32_16x16x32_bf16 v[74:77], v[162:165], v[210:213], v[74:77]
	v_mfma_f32_16x16x32_bf16 v[74:77], v[166:169], v[214:217], v[74:77]
	v_mfma_f32_16x16x32_bf16 v[126:129], v[170:173], v[178:181], v[126:129]
	v_mfma_f32_16x16x32_bf16 v[126:129], v[174:177], v[182:185], v[126:129]
	v_mfma_f32_16x16x32_bf16 v[110:113], v[170:173], v[186:189], v[110:113]
	v_mfma_f32_16x16x32_bf16 v[110:113], v[174:177], v[190:193], v[110:113]
	v_mfma_f32_16x16x32_bf16 v[94:97], v[170:173], v[202:205], v[94:97]
	v_mfma_f32_16x16x32_bf16 v[94:97], v[174:177], v[206:209], v[94:97]
	v_mfma_f32_16x16x32_bf16 v[78:81], v[170:173], v[210:213], v[78:81]
	v_mfma_f32_16x16x32_bf16 v[78:81], v[174:177], v[214:217], v[78:81]
	s_barrier
	s_setprio 0
	s_add_i32 s38, s39, s27
	v_lshl_add_u64 v[194:195], s[56:57], 0, v[0:1]
	s_mov_b32 m0, s38
	ds_read_b128 v[178:181], v144 offset:16384
	ds_read_b128 v[182:185], v144 offset:17408
	ds_read_b128 v[186:189], v144 offset:18432
	ds_read_b128 v[190:193], v144 offset:19456
	ds_read_b128 v[202:205], v144 offset:20480
	ds_read_b128 v[206:209], v144 offset:21504
	ds_read_b128 v[210:213], v144 offset:22528
	ds_read_b128 v[214:217], v144 offset:23552
	global_load_lds_dwordx4 v[194:195], off
	s_add_i32 m0, s38, 0x2000
	s_add_u32 s38, s56, 0x40000
	v_lshl_add_u64 v[218:219], s[56:57], 0, v[130:131]
	s_addc_u32 s39, s57, 0
	s_add_i32 s18, s18, s27
	global_load_lds_dwordx4 v[218:219], off
	v_lshl_add_u64 v[220:221], s[38:39], 0, v[0:1]
	s_mov_b32 m0, s18
	v_lshl_add_u64 v[222:223], s[64:65], 0, v[132:133]
	global_load_lds_dwordx4 v[220:221], off
	v_lshl_add_u64 v[220:221], s[38:39], 0, v[130:131]
	s_add_i32 m0, s18, 0x2000
	s_nop 0
	global_load_lds_dwordx4 v[220:221], off
	v_lshl_add_u64 v[220:221], s[64:65], 0, v[134:135]
	s_mov_b32 m0, s29
	s_nop 0
	global_load_lds_dwordx4 v[220:221], off
	s_mov_b32 m0, s33
	s_nop 0
	global_load_lds_dwordx4 v[222:223], off
	s_waitcnt vmcnt(8)
	s_waitcnt lgkmcnt(0)
	s_barrier
; #define PG8_STAGE(bufoff, gbase, voff) do { _Pragma("unroll") for (int _i = 0; _i < 2; ++_i) \
;         __builtin_amdgcn_global_load_lds((const unsigned*)((const char*)(gbase) + (voff)[_i]), (PG8_LAS unsigned*)(lds + (bufoff) + ldsw + _i * 8192), 16, 0, 0); } while (0)
; #define PG8_LDA(dst, b, h) do { _Pragma("unroll") for (int m = 0; m < 4; ++m) _Pragma("unroll") for (int k = 0; k < 2; ++k) dst[m][k] = *(const PG8_LAS bf16x8*)(lds + PG8_SA(b, h) + aoff + m * 2048 + k * 1024); } while (0)
; #define PG8_LDB(dst, b, h) do { _Pragma("unroll") for (int n = 0; n < 2; ++n) _Pragma("unroll") for (int k = 0; k < 2; ++k) dst[n][k] = *(const PG8_LAS bf16x8*)(lds + PG8_SB(b, h) + boff + n * 2048 + k * 1024); } while (0)
; #define PG8_MMA(ai, bj, At, Bt) do { __builtin_amdgcn_s_setprio(1); _Pragma("unroll") for (int m = 0; m < 4; ++m) _Pragma("unroll") for (int n = 0; n < 2; ++n) _Pragma("unroll") for (int k = 0; k < 2; ++k) \
;         acc[ai][bj][m][n] = __builtin_amdgcn_mfma_f32_16x16x32_bf16(Bt[n][k], At[m][k], acc[ai][bj][m][n], 0, 0, 0); __builtin_amdgcn_s_setprio(0); } while (0)
; #define PG8_WAIT_V(n) asm volatile("s_waitcnt vmcnt(" #n ")" ::: "memory")
; #define PG8_WAIT_L(n) asm volatile("s_waitcnt lgkmcnt(" #n ")" ::: "memory")
; #define PG8_BAR __builtin_amdgcn_s_barrier()
; #define PG8_SCHED __builtin_amdgcn_sched_barrier(0)
; template <class Epi, class Sched, bool ALIGN_EPI = false, bool SP2 = false>
; __device__ __forceinline__ void gemm_phase(PG8_LAS unsigned char* lds, const Gemm g, const Sched& S, const Epi& E) {
;     ...
;             PG8_WAIT_V(8); PG8_WAIT_L(0); PG8_BAR; PG8_MMA(1, 0, At, B0); PG8_MMA(1, 1, At, B1); PG8_BAR; PG8_SCHED;
;             PG8_LDB(B0, 1, 0); PG8_LDB(B1, 1, 1); PG8_SCHED; PG8_LDA(At, 1, 0); PG8_STAGE(PG8_SA(0, 1), a2 + hstep, voffA);
;             PG8_WAIT_V(8); PG8_WAIT_L(0); PG8_BAR; PG8_MMA(0, 0, At, B0); PG8_MMA(0, 1, At, B1); PG8_BAR; PG8_SCHED;
	s_setprio 1
	v_mfma_f32_16x16x32_bf16 v[50:53], v[146:149], v[178:181], v[50:53]
	v_mfma_f32_16x16x32_bf16 v[50:53], v[150:153], v[182:185], v[50:53]
	v_mfma_f32_16x16x32_bf16 v[34:37], v[146:149], v[186:189], v[34:37]
	v_mfma_f32_16x16x32_bf16 v[34:37], v[150:153], v[190:193], v[34:37]
	v_mfma_f32_16x16x32_bf16 v[18:21], v[146:149], v[202:205], v[18:21]
	v_mfma_f32_16x16x32_bf16 v[18:21], v[150:153], v[206:209], v[18:21]
	v_mfma_f32_16x16x32_bf16 v[2:5], v[146:149], v[210:213], v[2:5]
	v_mfma_f32_16x16x32_bf16 v[2:5], v[150:153], v[214:217], v[2:5]
	v_mfma_f32_16x16x32_bf16 v[54:57], v[154:157], v[178:181], v[54:57]
	v_mfma_f32_16x16x32_bf16 v[54:57], v[158:161], v[182:185], v[54:57]
	v_mfma_f32_16x16x32_bf16 v[38:41], v[154:157], v[186:189], v[38:41]
	v_mfma_f32_16x16x32_bf16 v[38:41], v[158:161], v[190:193], v[38:41]
	v_mfma_f32_16x16x32_bf16 v[22:25], v[154:157], v[202:205], v[22:25]
	v_mfma_f32_16x16x32_bf16 v[22:25], v[158:161], v[206:209], v[22:25]
	v_mfma_f32_16x16x32_bf16 v[6:9], v[154:157], v[210:213], v[6:9]
	v_mfma_f32_16x16x32_bf16 v[6:9], v[158:161], v[214:217], v[6:9]
	v_mfma_f32_16x16x32_bf16 v[58:61], v[162:165], v[178:181], v[58:61]
	v_mfma_f32_16x16x32_bf16 v[58:61], v[166:169], v[182:185], v[58:61]
	v_mfma_f32_16x16x32_bf16 v[42:45], v[162:165], v[186:189], v[42:45]
	v_mfma_f32_16x16x32_bf16 v[42:45], v[166:169], v[190:193], v[42:45]
	v_mfma_f32_16x16x32_bf16 v[26:29], v[162:165], v[202:205], v[26:29]
	v_mfma_f32_16x16x32_bf16 v[26:29], v[166:169], v[206:209], v[26:29]
	v_mfma_f32_16x16x32_bf16 v[10:13], v[162:165], v[210:213], v[10:13]
	v_mfma_f32_16x16x32_bf16 v[10:13], v[166:169], v[214:217], v[10:13]
	v_mfma_f32_16x16x32_bf16 v[62:65], v[170:173], v[178:181], v[62:65]
	v_mfma_f32_16x16x32_bf16 v[62:65], v[174:177], v[182:185], v[62:65]
	v_mfma_f32_16x16x32_bf16 v[46:49], v[170:173], v[186:189], v[46:49]
	v_mfma_f32_16x16x32_bf16 v[46:49], v[174:177], v[190:193], v[46:49]
	v_mfma_f32_16x16x32_bf16 v[30:33], v[170:173], v[202:205], v[30:33]
	v_mfma_f32_16x16x32_bf16 v[30:33], v[174:177], v[206:209], v[30:33]
	v_mfma_f32_16x16x32_bf16 v[14:17], v[170:173], v[210:213], v[14:17]
	v_mfma_f32_16x16x32_bf16 v[14:17], v[174:177], v[214:217], v[14:17]
	s_barrier
	s_setprio 0
	s_add_i32 s18, 0, 0x18000
	v_add_u32_e32 v145, s18, v141
	s_add_i32 s83, 0, 0x1c000
	ds_read_b128 v[146:149], v145
	ds_read_b128 v[150:153], v145 offset:1024
	ds_read_b128 v[154:157], v145 offset:2048
	ds_read_b128 v[158:161], v145 offset:3072
	v_add_u32_e32 v145, s83, v141
	ds_read_b128 v[162:165], v145
	ds_read_b128 v[166:169], v145 offset:1024
	ds_read_b128 v[170:173], v145 offset:2048
	ds_read_b128 v[174:177], v145 offset:3072
	s_add_u32 s38, s64, 0x40000
	s_addc_u32 s39, s65, 0
	s_mov_b32 m0, s58
	v_lshl_add_u64 v[224:225], s[38:39], 0, v[134:135]
	ds_read_b128 v[178:181], v144 offset:32768
	ds_read_b128 v[182:185], v144 offset:33792
	ds_read_b128 v[186:189], v144 offset:34816
	ds_read_b128 v[190:193], v144 offset:35840
	ds_read_b128 v[202:205], v144 offset:36864
	ds_read_b128 v[206:209], v144 offset:37888
	ds_read_b128 v[210:213], v144 offset:38912
	ds_read_b128 v[214:217], v144 offset:39936
	global_load_lds_dwordx4 v[224:225], off
	v_lshl_add_u64 v[224:225], s[38:39], 0, v[132:133]
	s_mov_b32 m0, s69
	s_nop 0
	global_load_lds_dwordx4 v[224:225], off
	s_waitcnt vmcnt(8)
	s_waitcnt lgkmcnt(0)
	s_barrier
	s_setprio 1
	v_mfma_f32_16x16x32_bf16 v[114:117], v[146:149], v[178:181], v[114:117]
	v_mfma_f32_16x16x32_bf16 v[114:117], v[150:153], v[182:185], v[114:117]
	v_mfma_f32_16x16x32_bf16 v[98:101], v[146:149], v[186:189], v[98:101]
	v_mfma_f32_16x16x32_bf16 v[98:101], v[150:153], v[190:193], v[98:101]
	v_mfma_f32_16x16x32_bf16 v[82:85], v[146:149], v[202:205], v[82:85]
	v_mfma_f32_16x16x32_bf16 v[82:85], v[150:153], v[206:209], v[82:85]
	v_mfma_f32_16x16x32_bf16 v[66:69], v[146:149], v[210:213], v[66:69]
	v_mfma_f32_16x16x32_bf16 v[66:69], v[150:153], v[214:217], v[66:69]
	v_mfma_f32_16x16x32_bf16 v[118:121], v[154:157], v[178:181], v[118:121]
	v_mfma_f32_16x16x32_bf16 v[118:121], v[158:161], v[182:185], v[118:121]
	v_mfma_f32_16x16x32_bf16 v[102:105], v[154:157], v[186:189], v[102:105]
	v_mfma_f32_16x16x32_bf16 v[102:105], v[158:161], v[190:193], v[102:105]
	v_mfma_f32_16x16x32_bf16 v[86:89], v[154:157], v[202:205], v[86:89]
	v_mfma_f32_16x16x32_bf16 v[86:89], v[158:161], v[206:209], v[86:89]
	v_mfma_f32_16x16x32_bf16 v[70:73], v[154:157], v[210:213], v[70:73]
	v_mfma_f32_16x16x32_bf16 v[70:73], v[158:161], v[214:217], v[70:73]
	v_mfma_f32_16x16x32_bf16 v[122:125], v[162:165], v[178:181], v[122:125]
	v_mfma_f32_16x16x32_bf16 v[122:125], v[166:169], v[182:185], v[122:125]
	v_mfma_f32_16x16x32_bf16 v[106:109], v[162:165], v[186:189], v[106:109]
	v_mfma_f32_16x16x32_bf16 v[106:109], v[166:169], v[190:193], v[106:109]
	v_mfma_f32_16x16x32_bf16 v[90:93], v[162:165], v[202:205], v[90:93]
	v_mfma_f32_16x16x32_bf16 v[90:93], v[166:169], v[206:209], v[90:93]
	v_mfma_f32_16x16x32_bf16 v[74:77], v[162:165], v[210:213], v[74:77]
	v_mfma_f32_16x16x32_bf16 v[74:77], v[166:169], v[214:217], v[74:77]
	v_mfma_f32_16x16x32_bf16 v[126:129], v[170:173], v[178:181], v[126:129]
	v_mfma_f32_16x16x32_bf16 v[126:129], v[174:177], v[182:185], v[126:129]
	v_mfma_f32_16x16x32_bf16 v[110:113], v[170:173], v[186:189], v[110:113]
	v_mfma_f32_16x16x32_bf16 v[110:113], v[174:177], v[190:193], v[110:113]
	v_mfma_f32_16x16x32_bf16 v[94:97], v[170:173], v[202:205], v[94:97]
	v_mfma_f32_16x16x32_bf16 v[94:97], v[174:177], v[206:209], v[94:97]
	v_mfma_f32_16x16x32_bf16 v[78:81], v[170:173], v[210:213], v[78:81]
	v_mfma_f32_16x16x32_bf16 v[78:81], v[174:177], v[214:217], v[78:81]
	s_barrier
; #define PG8_STAGE(bufoff, gbase, voff) do { _Pragma("unroll") for (int _i = 0; _i < 2; ++_i) \
;         __builtin_amdgcn_global_load_lds((const unsigned*)((const char*)(gbase) + (voff)[_i]), (PG8_LAS unsigned*)(lds + (bufoff) + ldsw + _i * 8192), 16, 0, 0); } while (0)
; #define PG8_LDA(dst, b, h) do { _Pragma("unroll") for (int m = 0; m < 4; ++m) _Pragma("unroll") for (int k = 0; k < 2; ++k) dst[m][k] = *(const PG8_LAS bf16x8*)(lds + PG8_SA(b, h) + aoff + m * 2048 + k * 1024); } while (0)
; #define PG8_MMA(ai, bj, At, Bt) do { __builtin_amdgcn_s_setprio(1); _Pragma("unroll") for (int m = 0; m < 4; ++m) _Pragma("unroll") for (int n = 0; n < 2; ++n) _Pragma("unroll") for (int k = 0; k < 2; ++k) \
;         acc[ai][bj][m][n] = __builtin_amdgcn_mfma_f32_16x16x32_bf16(Bt[n][k], At[m][k], acc[ai][bj][m][n], 0, 0, 0); __builtin_amdgcn_s_setprio(0); } while (0)
; #define PG8_WAIT_V(n) asm volatile("s_waitcnt vmcnt(" #n ")" ::: "memory")
; #define PG8_WAIT_L(n) asm volatile("s_waitcnt lgkmcnt(" #n ")" ::: "memory")
; #define PG8_BAR __builtin_amdgcn_s_barrier()
; #define PG8_SCHED __builtin_amdgcn_sched_barrier(0)
; template <class Epi, class Sched, bool ALIGN_EPI = false, bool SP2 = false>
; __device__ __forceinline__ void gemm_phase(PG8_LAS unsigned char* lds, const Gemm g, const Sched& S, const Epi& E) {
;     ...
;         for (int t = 0; t < nt; t += 2) {
;             const bool last = (t == nt - 2);
;     ...
;             PG8_LDA(At, 1, 1); PG8_STAGE(PG8_SB(1, 0), b3, voffB); PG8_STAGE(PG8_SB(1, 1), b3 + hstep, voffB); PG8_STAGE(PG8_SA(1, 0), a3, voffA);
;             PG8_WAIT_V(8); PG8_WAIT_L(0); PG8_BAR; PG8_MMA(1, 0, At, B0); PG8_MMA(1, 1, At, B1); PG8_BAR; PG8_SCHED;
	s_setprio 0
	s_add_i32 s18, s18, s27
	v_lshl_add_u64 v[194:195], v[194:195], 0, s[30:31]
	s_mov_b32 m0, s18
	ds_read_b128 v[178:181], v144 offset:49152
	ds_read_b128 v[182:185], v144 offset:50176
	ds_read_b128 v[186:189], v144 offset:51200
	ds_read_b128 v[190:193], v144 offset:52224
	ds_read_b128 v[202:205], v144 offset:53248
	ds_read_b128 v[206:209], v144 offset:54272
	ds_read_b128 v[210:213], v144 offset:55296
	ds_read_b128 v[214:217], v144 offset:56320
	global_load_lds_dwordx4 v[194:195], off
	s_add_i32 m0, s18, 0x2000
	s_add_u32 s38, s56, 0x40080
	v_lshl_add_u64 v[194:195], v[218:219], 0, s[30:31]
	s_addc_u32 s39, s57, 0
	s_add_i32 s18, s83, s27
	global_load_lds_dwordx4 v[194:195], off
	v_lshl_add_u64 v[194:195], s[38:39], 0, v[0:1]
	s_mov_b32 m0, s18
	s_nop 0
	global_load_lds_dwordx4 v[194:195], off
	v_lshl_add_u64 v[194:195], s[38:39], 0, v[130:131]
	s_add_i32 m0, s18, 0x2000
	s_nop 0
	global_load_lds_dwordx4 v[194:195], off
	v_lshl_add_u64 v[194:195], v[220:221], 0, s[30:31]
	s_mov_b32 m0, s71
	s_nop 0
	global_load_lds_dwordx4 v[194:195], off
	v_lshl_add_u64 v[194:195], v[222:223], 0, s[30:31]
	s_mov_b32 m0, s72
	s_nop 0
	global_load_lds_dwordx4 v[194:195], off
	s_waitcnt vmcnt(8)
	s_waitcnt lgkmcnt(0)
	s_barrier
	s_setprio 1
	v_mfma_f32_16x16x32_bf16 v[50:53], v[146:149], v[178:181], v[50:53]
	v_mfma_f32_16x16x32_bf16 v[50:53], v[150:153], v[182:185], v[50:53]
	v_mfma_f32_16x16x32_bf16 v[34:37], v[146:149], v[186:189], v[34:37]
	v_mfma_f32_16x16x32_bf16 v[34:37], v[150:153], v[190:193], v[34:37]
	v_mfma_f32_16x16x32_bf16 v[18:21], v[146:149], v[202:205], v[18:21]
	v_mfma_f32_16x16x32_bf16 v[18:21], v[150:153], v[206:209], v[18:21]
	v_mfma_f32_16x16x32_bf16 v[2:5], v[146:149], v[210:213], v[2:5]
	v_mfma_f32_16x16x32_bf16 v[2:5], v[150:153], v[214:217], v[2:5]
	v_mfma_f32_16x16x32_bf16 v[54:57], v[154:157], v[178:181], v[54:57]
	v_mfma_f32_16x16x32_bf16 v[54:57], v[158:161], v[182:185], v[54:57]
	v_mfma_f32_16x16x32_bf16 v[38:41], v[154:157], v[186:189], v[38:41]
	v_mfma_f32_16x16x32_bf16 v[38:41], v[158:161], v[190:193], v[38:41]
	v_mfma_f32_16x16x32_bf16 v[22:25], v[154:157], v[202:205], v[22:25]
	v_mfma_f32_16x16x32_bf16 v[22:25], v[158:161], v[206:209], v[22:25]
	v_mfma_f32_16x16x32_bf16 v[6:9], v[154:157], v[210:213], v[6:9]
	v_mfma_f32_16x16x32_bf16 v[6:9], v[158:161], v[214:217], v[6:9]
	v_mfma_f32_16x16x32_bf16 v[58:61], v[162:165], v[178:181], v[58:61]
	v_mfma_f32_16x16x32_bf16 v[58:61], v[166:169], v[182:185], v[58:61]
	v_mfma_f32_16x16x32_bf16 v[42:45], v[162:165], v[186:189], v[42:45]
	v_mfma_f32_16x16x32_bf16 v[42:45], v[166:169], v[190:193], v[42:45]
	v_mfma_f32_16x16x32_bf16 v[26:29], v[162:165], v[202:205], v[26:29]
	v_mfma_f32_16x16x32_bf16 v[26:29], v[166:169], v[206:209], v[26:29]
	v_mfma_f32_16x16x32_bf16 v[10:13], v[162:165], v[210:213], v[10:13]
	v_mfma_f32_16x16x32_bf16 v[10:13], v[166:169], v[214:217], v[10:13]
	v_mfma_f32_16x16x32_bf16 v[62:65], v[170:173], v[178:181], v[62:65]
	v_mfma_f32_16x16x32_bf16 v[62:65], v[174:177], v[182:185], v[62:65]
	v_mfma_f32_16x16x32_bf16 v[46:49], v[170:173], v[186:189], v[46:49]
	v_mfma_f32_16x16x32_bf16 v[46:49], v[174:177], v[190:193], v[46:49]
	v_mfma_f32_16x16x32_bf16 v[30:33], v[170:173], v[202:205], v[30:33]
	v_mfma_f32_16x16x32_bf16 v[30:33], v[174:177], v[206:209], v[30:33]
	v_mfma_f32_16x16x32_bf16 v[14:17], v[170:173], v[210:213], v[14:17]
	v_mfma_f32_16x16x32_bf16 v[14:17], v[174:177], v[214:217], v[14:17]
	s_barrier
	s_setprio 0
	s_add_i32 s82, s82, 2
	s_add_u32 s60, s60, 0x100
	s_addc_u32 s61, s61, 0
	s_add_u32 s80, s80, 0x100
	s_addc_u32 s81, s81, 0
	s_cmp_gt_u32 s82, 13
	s_cbranch_scc0 .LBB0_220
	s_and_b64 vcc, exec, s[44:45]
	s_cbranch_vccz .LBB0_223
	s_barrier

; #define PG8_STAGE(bufoff, gbase, voff) do { _Pragma("unroll") for (int _i = 0; _i < 2; ++_i) \
;         __builtin_amdgcn_global_load_lds((const unsigned*)((const char*)(gbase) + (voff)[_i]), (PG8_LAS unsigned*)(lds + (bufoff) + ldsw + _i * 8192), 16, 0, 0); } while (0)
; #define PG8_LDA(dst, b, h) do { _Pragma("unroll") for (int m = 0; m < 4; ++m) _Pragma("unroll") for (int k = 0; k < 2; ++k) dst[m][k] = *(const PG8_LAS bf16x8*)(lds + PG8_SA(b, h) + aoff + m * 2048 + k * 1024); } while (0)
; #define PG8_LDB(dst, b, h) do { _Pragma("unroll") for (int n = 0; n < 2; ++n) _Pragma("unroll") for (int k = 0; k < 2; ++k) dst[n][k] = *(const PG8_LAS bf16x8*)(lds + PG8_SB(b, h) + boff + n * 2048 + k * 1024); } while (0)
; #define PG8_MMA(ai, bj, At, Bt) do { __builtin_amdgcn_s_setprio(1); _Pragma("unroll") for (int m = 0; m < 4; ++m) _Pragma("unroll") for (int n = 0; n < 2; ++n) _Pragma("unroll") for (int k = 0; k < 2; ++k) \
;         acc[ai][bj][m][n] = __builtin_amdgcn_mfma_f32_16x16x32_bf16(Bt[n][k], At[m][k], acc[ai][bj][m][n], 0, 0, 0); __builtin_amdgcn_s_setprio(0); } while (0)
; #define PG8_WAIT_V(n) asm volatile("s_waitcnt vmcnt(" #n ")" ::: "memory")
; #define PG8_WAIT_L(n) asm volatile("s_waitcnt lgkmcnt(" #n ")" ::: "memory")
; #define PG8_BAR __builtin_amdgcn_s_barrier()
; #define PG8_SCHED __builtin_amdgcn_sched_barrier(0)
; template <class Epi, class Sched, bool ALIGN_EPI = false, bool SP2 = false>
; __device__ __forceinline__ void gemm_phase(PG8_LAS unsigned char* lds, const Gemm g, const Sched& S, const Epi& E) {
;     ...
;             PG8_LDB(B0, 0, 0); PG8_LDB(B1, 0, 1); PG8_SCHED; PG8_LDA(At, 0, 0); PG8_STAGE(PG8_SA(1, 1), a1 + hstep, voffA);
;             PG8_WAIT_V(8); PG8_WAIT_L(0); PG8_BAR; PG8_MMA(0, 0, At, B0); PG8_MMA(0, 1, At, B1); PG8_BAR; PG8_SCHED;
;             PG8_LDA(At, 0, 1); PG8_STAGE(PG8_SB(0, 0), b2, voffB); PG8_STAGE(PG8_SB(0, 1), b2 + hstep, voffB); PG8_STAGE(PG8_SA(0, 0), a2, voffA);
;             PG8_WAIT_V(8); PG8_WAIT_L(0); PG8_BAR; PG8_MMA(1, 0, At, B0); PG8_MMA(1, 1, At, B1); PG8_BAR; PG8_SCHED;
.LBB0_274:
	s_add_i32 vcc_lo, s46, 2
	s_add_u32 s38, s48, 0x80
	s_addc_u32 s39, s49, 0
	s_add_i32 vcc_hi, 0, 0x10000
	s_cmp_eq_u32 s99, s46
	s_cselect_b32 s47, s81, s39
	s_cselect_b32 s46, s80, s38
	s_cselect_b32 s39, s83, s51
	s_cselect_b32 s38, s82, s50
	s_add_i32 s18, 0, 0x14000
	v_add_u32_e32 v142, vcc_hi, v245
	v_add_u32_e32 v158, s18, v245
	ds_read_b128 v[110:113], v142
	ds_read_b128 v[118:121], v142 offset:1024
	ds_read_b128 v[138:141], v142 offset:2048
	ds_read_b128 v[142:145], v142 offset:3072
	ds_read_b128 v[146:149], v158
	ds_read_b128 v[150:153], v158 offset:1024
	ds_read_b128 v[154:157], v158 offset:2048
	ds_read_b128 v[158:161], v158 offset:3072
	v_lshl_add_u64 v[210:211], s[48:49], 0, v[206:207]
	s_add_i32 m0, s92, 0xc000
	ds_read_b128 v[162:165], v247
	ds_read_b128 v[166:169], v247 offset:1024
	ds_read_b128 v[170:173], v247 offset:2048
	ds_read_b128 v[174:177], v247 offset:3072
	ds_read_b128 v[178:181], v247 offset:4096
	ds_read_b128 v[182:185], v247 offset:5120
	ds_read_b128 v[186:189], v247 offset:6144
	ds_read_b128 v[190:193], v247 offset:7168
	global_load_lds_dwordx4 v[210:211], off
	v_lshl_add_u64 v[210:211], s[48:49], 0, v[208:209]
	s_add_i32 m0, s92, 0xe000
	s_nop 0
	global_load_lds_dwordx4 v[210:211], off
	s_waitcnt vmcnt(8)
	s_waitcnt lgkmcnt(0)
	s_barrier
	s_setprio 1
	v_mfma_f32_16x16x32_bf16 v[130:133], v[110:113], v[162:165], v[130:133]
	v_mfma_f32_16x16x32_bf16 v[130:133], v[118:121], v[166:169], v[130:133]
	v_mfma_f32_16x16x32_bf16 v[114:117], v[110:113], v[170:173], v[114:117]
	v_mfma_f32_16x16x32_bf16 v[114:117], v[118:121], v[174:177], v[114:117]
	v_mfma_f32_16x16x32_bf16 v[94:97], v[110:113], v[178:181], v[94:97]
	v_mfma_f32_16x16x32_bf16 v[94:97], v[118:121], v[182:185], v[94:97]
	v_mfma_f32_16x16x32_bf16 v[78:81], v[110:113], v[186:189], v[78:81]
	v_mfma_f32_16x16x32_bf16 v[78:81], v[118:121], v[190:193], v[78:81]
	v_mfma_f32_16x16x32_bf16 v[134:137], v[138:141], v[162:165], v[134:137]
	v_mfma_f32_16x16x32_bf16 v[134:137], v[142:145], v[166:169], v[134:137]
	v_mfma_f32_16x16x32_bf16 v[106:109], v[138:141], v[170:173], v[106:109]
	v_mfma_f32_16x16x32_bf16 v[106:109], v[142:145], v[174:177], v[106:109]
	v_mfma_f32_16x16x32_bf16 v[90:93], v[138:141], v[178:181], v[90:93]
	v_mfma_f32_16x16x32_bf16 v[90:93], v[142:145], v[182:185], v[90:93]
	v_mfma_f32_16x16x32_bf16 v[74:77], v[138:141], v[186:189], v[74:77]
	v_mfma_f32_16x16x32_bf16 v[74:77], v[142:145], v[190:193], v[74:77]
	v_mfma_f32_16x16x32_bf16 v[126:129], v[146:149], v[162:165], v[126:129]
	v_mfma_f32_16x16x32_bf16 v[126:129], v[150:153], v[166:169], v[126:129]
	v_mfma_f32_16x16x32_bf16 v[102:105], v[146:149], v[170:173], v[102:105]
	v_mfma_f32_16x16x32_bf16 v[102:105], v[150:153], v[174:177], v[102:105]
	v_mfma_f32_16x16x32_bf16 v[86:89], v[146:149], v[178:181], v[86:89]
	v_mfma_f32_16x16x32_bf16 v[86:89], v[150:153], v[182:185], v[86:89]
	v_mfma_f32_16x16x32_bf16 v[70:73], v[146:149], v[186:189], v[70:73]
	v_mfma_f32_16x16x32_bf16 v[70:73], v[150:153], v[190:193], v[70:73]
	v_mfma_f32_16x16x32_bf16 v[122:125], v[154:157], v[162:165], v[122:125]
	v_mfma_f32_16x16x32_bf16 v[122:125], v[158:161], v[166:169], v[122:125]
	v_mfma_f32_16x16x32_bf16 v[98:101], v[154:157], v[170:173], v[98:101]
	v_mfma_f32_16x16x32_bf16 v[98:101], v[158:161], v[174:177], v[98:101]
	v_mfma_f32_16x16x32_bf16 v[82:85], v[154:157], v[178:181], v[82:85]
	v_mfma_f32_16x16x32_bf16 v[82:85], v[158:161], v[182:185], v[82:85]
	v_mfma_f32_16x16x32_bf16 v[66:69], v[154:157], v[186:189], v[66:69]
	v_mfma_f32_16x16x32_bf16 v[66:69], v[158:161], v[190:193], v[66:69]
	s_barrier
	s_setprio 0
	s_add_i32 vcc_hi, vcc_hi, s6
	v_lshl_add_u64 v[210:211], s[38:39], 0, v[0:1]
	s_mov_b32 m0, vcc_hi
	ds_read_b128 v[162:165], v247 offset:16384
	ds_read_b128 v[166:169], v247 offset:17408
	ds_read_b128 v[170:173], v247 offset:18432
	ds_read_b128 v[174:177], v247 offset:19456
	ds_read_b128 v[178:181], v247 offset:20480
	ds_read_b128 v[182:185], v247 offset:21504
	ds_read_b128 v[186:189], v247 offset:22528
	ds_read_b128 v[190:193], v247 offset:23552
	global_load_lds_dwordx4 v[210:211], off
	s_add_i32 m0, vcc_hi, 0x2000
	v_lshl_add_u64 v[212:213], s[38:39], 0, v[204:205]
	s_add_u32 s38, s38, s58
	s_addc_u32 s39, s39, 0
	s_add_i32 s18, s18, s6
	global_load_lds_dwordx4 v[212:213], off
	v_lshl_add_u64 v[214:215], s[38:39], 0, v[0:1]
	s_mov_b32 m0, s18
	v_lshl_add_u64 v[216:217], s[38:39], 0, v[204:205]
	global_load_lds_dwordx4 v[214:215], off
	s_add_i32 m0, s18, 0x2000
	v_lshl_add_u64 v[218:219], s[46:47], 0, v[194:195]
	global_load_lds_dwordx4 v[216:217], off
	s_mov_b32 m0, s92
	v_lshl_add_u64 v[220:221], s[46:47], 0, v[202:203]
	global_load_lds_dwordx4 v[218:219], off
	s_mov_b32 m0, s93
	s_nop 0
	global_load_lds_dwordx4 v[220:221], off
	s_waitcnt vmcnt(8)
	s_waitcnt lgkmcnt(0)
	s_barrier
; #define PG8_STAGE(bufoff, gbase, voff) do { _Pragma("unroll") for (int _i = 0; _i < 2; ++_i) \
;         __builtin_amdgcn_global_load_lds((const unsigned*)((const char*)(gbase) + (voff)[_i]), (PG8_LAS unsigned*)(lds + (bufoff) + ldsw + _i * 8192), 16, 0, 0); } while (0)
; #define PG8_LDA(dst, b, h) do { _Pragma("unroll") for (int m = 0; m < 4; ++m) _Pragma("unroll") for (int k = 0; k < 2; ++k) dst[m][k] = *(const PG8_LAS bf16x8*)(lds + PG8_SA(b, h) + aoff + m * 2048 + k * 1024); } while (0)
; #define PG8_LDB(dst, b, h) do { _Pragma("unroll") for (int n = 0; n < 2; ++n) _Pragma("unroll") for (int k = 0; k < 2; ++k) dst[n][k] = *(const PG8_LAS bf16x8*)(lds + PG8_SB(b, h) + boff + n * 2048 + k * 1024); } while (0)
; #define PG8_MMA(ai, bj, At, Bt) do { __builtin_amdgcn_s_setprio(1); _Pragma("unroll") for (int m = 0; m < 4; ++m) _Pragma("unroll") for (int n = 0; n < 2; ++n) _Pragma("unroll") for (int k = 0; k < 2; ++k) \
;         acc[ai][bj][m][n] = __builtin_amdgcn_mfma_f32_16x16x32_bf16(Bt[n][k], At[m][k], acc[ai][bj][m][n], 0, 0, 0); __builtin_amdgcn_s_setprio(0); } while (0)
; #define PG8_WAIT_V(n) asm volatile("s_waitcnt vmcnt(" #n ")" ::: "memory")
; #define PG8_WAIT_L(n) asm volatile("s_waitcnt lgkmcnt(" #n ")" ::: "memory")
; #define PG8_BAR __builtin_amdgcn_s_barrier()
; #define PG8_SCHED __builtin_amdgcn_sched_barrier(0)
; template <class Epi, class Sched, bool ALIGN_EPI = false, bool SP2 = false>
; __device__ __forceinline__ void gemm_phase(PG8_LAS unsigned char* lds, const Gemm g, const Sched& S, const Epi& E) {
;     ...
;             PG8_WAIT_V(8); PG8_WAIT_L(0); PG8_BAR; PG8_MMA(1, 0, At, B0); PG8_MMA(1, 1, At, B1); PG8_BAR; PG8_SCHED;
;             PG8_LDB(B0, 1, 0); PG8_LDB(B1, 1, 1); PG8_SCHED; PG8_LDA(At, 1, 0); PG8_STAGE(PG8_SA(0, 1), a2 + hstep, voffA);
;             PG8_WAIT_V(8); PG8_WAIT_L(0); PG8_BAR; PG8_MMA(0, 0, At, B0); PG8_MMA(0, 1, At, B1); PG8_BAR; PG8_SCHED;
	s_setprio 1
	v_mfma_f32_16x16x32_bf16 v[62:65], v[110:113], v[162:165], v[62:65]
	v_mfma_f32_16x16x32_bf16 v[62:65], v[118:121], v[166:169], v[62:65]
	v_mfma_f32_16x16x32_bf16 v[46:49], v[110:113], v[170:173], v[46:49]
	v_mfma_f32_16x16x32_bf16 v[46:49], v[118:121], v[174:177], v[46:49]
	v_mfma_f32_16x16x32_bf16 v[30:33], v[110:113], v[178:181], v[30:33]
	v_mfma_f32_16x16x32_bf16 v[30:33], v[118:121], v[182:185], v[30:33]
	v_mfma_f32_16x16x32_bf16 v[14:17], v[110:113], v[186:189], v[14:17]
	v_mfma_f32_16x16x32_bf16 v[14:17], v[118:121], v[190:193], v[14:17]
	v_mfma_f32_16x16x32_bf16 v[58:61], v[138:141], v[162:165], v[58:61]
	v_mfma_f32_16x16x32_bf16 v[58:61], v[142:145], v[166:169], v[58:61]
	v_mfma_f32_16x16x32_bf16 v[42:45], v[138:141], v[170:173], v[42:45]
	v_mfma_f32_16x16x32_bf16 v[42:45], v[142:145], v[174:177], v[42:45]
	v_mfma_f32_16x16x32_bf16 v[26:29], v[138:141], v[178:181], v[26:29]
	v_mfma_f32_16x16x32_bf16 v[26:29], v[142:145], v[182:185], v[26:29]
	v_mfma_f32_16x16x32_bf16 v[10:13], v[138:141], v[186:189], v[10:13]
	v_mfma_f32_16x16x32_bf16 v[10:13], v[142:145], v[190:193], v[10:13]
	v_mfma_f32_16x16x32_bf16 v[54:57], v[146:149], v[162:165], v[54:57]
	v_mfma_f32_16x16x32_bf16 v[54:57], v[150:153], v[166:169], v[54:57]
	v_mfma_f32_16x16x32_bf16 v[38:41], v[146:149], v[170:173], v[38:41]
	v_mfma_f32_16x16x32_bf16 v[38:41], v[150:153], v[174:177], v[38:41]
	v_mfma_f32_16x16x32_bf16 v[22:25], v[146:149], v[178:181], v[22:25]
	v_mfma_f32_16x16x32_bf16 v[22:25], v[150:153], v[182:185], v[22:25]
	v_mfma_f32_16x16x32_bf16 v[6:9], v[146:149], v[186:189], v[6:9]
	v_mfma_f32_16x16x32_bf16 v[6:9], v[150:153], v[190:193], v[6:9]
	v_mfma_f32_16x16x32_bf16 v[50:53], v[154:157], v[162:165], v[50:53]
	v_mfma_f32_16x16x32_bf16 v[50:53], v[158:161], v[166:169], v[50:53]
	v_mfma_f32_16x16x32_bf16 v[34:37], v[154:157], v[170:173], v[34:37]
	v_mfma_f32_16x16x32_bf16 v[34:37], v[158:161], v[174:177], v[34:37]
	v_mfma_f32_16x16x32_bf16 v[18:21], v[154:157], v[178:181], v[18:21]
	v_mfma_f32_16x16x32_bf16 v[18:21], v[158:161], v[182:185], v[18:21]
	v_mfma_f32_16x16x32_bf16 v[2:5], v[154:157], v[186:189], v[2:5]
	v_mfma_f32_16x16x32_bf16 v[2:5], v[158:161], v[190:193], v[2:5]
	s_barrier
	s_setprio 0
	s_add_i32 s18, 0, 0x18000
	s_add_i32 vcc_hi, 0, 0x1c000
	v_add_u32_e32 v142, s18, v245
	v_add_u32_e32 v158, vcc_hi, v245
	ds_read_b128 v[110:113], v142
	ds_read_b128 v[118:121], v142 offset:1024
	ds_read_b128 v[138:141], v142 offset:2048
	ds_read_b128 v[142:145], v142 offset:3072
	ds_read_b128 v[146:149], v158
	ds_read_b128 v[150:153], v158 offset:1024
	ds_read_b128 v[154:157], v158 offset:2048
	ds_read_b128 v[158:161], v158 offset:3072
	s_add_u32 s38, s46, s58
	s_addc_u32 s39, s47, 0
	s_mov_b32 m0, s94
	v_lshl_add_u64 v[222:223], s[38:39], 0, v[194:195]
	ds_read_b128 v[162:165], v247 offset:32768
	ds_read_b128 v[166:169], v247 offset:33792
	ds_read_b128 v[170:173], v247 offset:34816
	ds_read_b128 v[174:177], v247 offset:35840
	ds_read_b128 v[178:181], v247 offset:36864
	ds_read_b128 v[182:185], v247 offset:37888
	ds_read_b128 v[186:189], v247 offset:38912
	ds_read_b128 v[190:193], v247 offset:39936
	global_load_lds_dwordx4 v[222:223], off
	v_lshl_add_u64 v[222:223], s[38:39], 0, v[202:203]
	s_mov_b32 m0, s95
	s_nop 0
	global_load_lds_dwordx4 v[222:223], off
	s_waitcnt vmcnt(8)
	s_waitcnt lgkmcnt(0)
	s_barrier
	s_setprio 1
	v_mfma_f32_16x16x32_bf16 v[130:133], v[110:113], v[162:165], v[130:133]
	v_mfma_f32_16x16x32_bf16 v[130:133], v[118:121], v[166:169], v[130:133]
	v_mfma_f32_16x16x32_bf16 v[114:117], v[110:113], v[170:173], v[114:117]
	v_mfma_f32_16x16x32_bf16 v[114:117], v[118:121], v[174:177], v[114:117]
	v_mfma_f32_16x16x32_bf16 v[94:97], v[110:113], v[178:181], v[94:97]
	v_mfma_f32_16x16x32_bf16 v[94:97], v[118:121], v[182:185], v[94:97]
	v_mfma_f32_16x16x32_bf16 v[78:81], v[110:113], v[186:189], v[78:81]
	v_mfma_f32_16x16x32_bf16 v[78:81], v[118:121], v[190:193], v[78:81]
	v_mfma_f32_16x16x32_bf16 v[134:137], v[138:141], v[162:165], v[134:137]
	v_mfma_f32_16x16x32_bf16 v[134:137], v[142:145], v[166:169], v[134:137]
	v_mfma_f32_16x16x32_bf16 v[106:109], v[138:141], v[170:173], v[106:109]
	v_mfma_f32_16x16x32_bf16 v[106:109], v[142:145], v[174:177], v[106:109]
	v_mfma_f32_16x16x32_bf16 v[90:93], v[138:141], v[178:181], v[90:93]
	v_mfma_f32_16x16x32_bf16 v[90:93], v[142:145], v[182:185], v[90:93]
	v_mfma_f32_16x16x32_bf16 v[74:77], v[138:141], v[186:189], v[74:77]
	v_mfma_f32_16x16x32_bf16 v[74:77], v[142:145], v[190:193], v[74:77]
	v_mfma_f32_16x16x32_bf16 v[126:129], v[146:149], v[162:165], v[126:129]
	v_mfma_f32_16x16x32_bf16 v[126:129], v[150:153], v[166:169], v[126:129]
	v_mfma_f32_16x16x32_bf16 v[102:105], v[146:149], v[170:173], v[102:105]
	v_mfma_f32_16x16x32_bf16 v[102:105], v[150:153], v[174:177], v[102:105]
	v_mfma_f32_16x16x32_bf16 v[86:89], v[146:149], v[178:181], v[86:89]
	v_mfma_f32_16x16x32_bf16 v[86:89], v[150:153], v[182:185], v[86:89]
	v_mfma_f32_16x16x32_bf16 v[70:73], v[146:149], v[186:189], v[70:73]
	v_mfma_f32_16x16x32_bf16 v[70:73], v[150:153], v[190:193], v[70:73]
	v_mfma_f32_16x16x32_bf16 v[122:125], v[154:157], v[162:165], v[122:125]
	v_mfma_f32_16x16x32_bf16 v[122:125], v[158:161], v[166:169], v[122:125]
	v_mfma_f32_16x16x32_bf16 v[98:101], v[154:157], v[170:173], v[98:101]
	v_mfma_f32_16x16x32_bf16 v[98:101], v[158:161], v[174:177], v[98:101]
	v_mfma_f32_16x16x32_bf16 v[82:85], v[154:157], v[178:181], v[82:85]
	v_mfma_f32_16x16x32_bf16 v[82:85], v[158:161], v[182:185], v[82:85]
	v_mfma_f32_16x16x32_bf16 v[66:69], v[154:157], v[186:189], v[66:69]
	v_mfma_f32_16x16x32_bf16 v[66:69], v[158:161], v[190:193], v[66:69]
	s_barrier
; #define PG8_STAGE(bufoff, gbase, voff) do { _Pragma("unroll") for (int _i = 0; _i < 2; ++_i) \
;         __builtin_amdgcn_global_load_lds((const unsigned*)((const char*)(gbase) + (voff)[_i]), (PG8_LAS unsigned*)(lds + (bufoff) + ldsw + _i * 8192), 16, 0, 0); } while (0)
; #define PG8_LDA(dst, b, h) do { _Pragma("unroll") for (int m = 0; m < 4; ++m) _Pragma("unroll") for (int k = 0; k < 2; ++k) dst[m][k] = *(const PG8_LAS bf16x8*)(lds + PG8_SA(b, h) + aoff + m * 2048 + k * 1024); } while (0)
; #define PG8_MMA(ai, bj, At, Bt) do { __builtin_amdgcn_s_setprio(1); _Pragma("unroll") for (int m = 0; m < 4; ++m) _Pragma("unroll") for (int n = 0; n < 2; ++n) _Pragma("unroll") for (int k = 0; k < 2; ++k) \
;         acc[ai][bj][m][n] = __builtin_amdgcn_mfma_f32_16x16x32_bf16(Bt[n][k], At[m][k], acc[ai][bj][m][n], 0, 0, 0); __builtin_amdgcn_s_setprio(0); } while (0)
; #define PG8_WAIT_V(n) asm volatile("s_waitcnt vmcnt(" #n ")" ::: "memory")
; #define PG8_WAIT_L(n) asm volatile("s_waitcnt lgkmcnt(" #n ")" ::: "memory")
; #define PG8_BAR __builtin_amdgcn_s_barrier()
; #define PG8_SCHED __builtin_amdgcn_sched_barrier(0)
; template <class Epi, class Sched, bool ALIGN_EPI = false, bool SP2 = false>
; __device__ __forceinline__ void gemm_phase(PG8_LAS unsigned char* lds, const Gemm g, const Sched& S, const Epi& E) {
;     ...
;             PG8_LDA(At, 1, 1); PG8_STAGE(PG8_SB(1, 0), b3, voffB); PG8_STAGE(PG8_SB(1, 1), b3 + hstep, voffB); PG8_STAGE(PG8_SA(1, 0), a3, voffA);
;             PG8_WAIT_V(8); PG8_WAIT_L(0); PG8_BAR; PG8_MMA(1, 0, At, B0); PG8_MMA(1, 1, At, B1); PG8_BAR; PG8_SCHED;
;     ...
;         if constexpr (ALIGN_EPI) { if (wr == 0) PG8_BAR; }
	s_setprio 0
	s_add_i32 s18, s18, s6
	v_lshl_add_u64 v[210:211], v[210:211], 0, s[30:31]
	s_mov_b32 m0, s18
	ds_read_b128 v[162:165], v247 offset:49152
	ds_read_b128 v[166:169], v247 offset:50176
	ds_read_b128 v[170:173], v247 offset:51200
	ds_read_b128 v[174:177], v247 offset:52224
	ds_read_b128 v[178:181], v247 offset:53248
	ds_read_b128 v[182:185], v247 offset:54272
	ds_read_b128 v[186:189], v247 offset:55296
	ds_read_b128 v[190:193], v247 offset:56320
	global_load_lds_dwordx4 v[210:211], off
	v_lshl_add_u64 v[210:211], v[212:213], 0, s[30:31]
	s_add_i32 m0, s18, 0x2000
	s_add_i32 s18, vcc_hi, s6
	global_load_lds_dwordx4 v[210:211], off
	v_lshl_add_u64 v[210:211], v[214:215], 0, s[30:31]
	s_mov_b32 m0, s18
	s_nop 0
	global_load_lds_dwordx4 v[210:211], off
	v_lshl_add_u64 v[210:211], v[216:217], 0, s[30:31]
	s_add_i32 m0, s18, 0x2000
	s_nop 0
	global_load_lds_dwordx4 v[210:211], off
	v_lshl_add_u64 v[210:211], v[218:219], 0, s[30:31]
	s_mov_b32 m0, s97
	s_nop 0
	global_load_lds_dwordx4 v[210:211], off
	v_lshl_add_u64 v[210:211], v[220:221], 0, s[30:31]
	s_mov_b32 m0, s98
	s_nop 0
	global_load_lds_dwordx4 v[210:211], off
	s_waitcnt vmcnt(8)
	s_waitcnt lgkmcnt(0)
	s_barrier
	s_setprio 1
	v_mfma_f32_16x16x32_bf16 v[62:65], v[110:113], v[162:165], v[62:65]
	v_mfma_f32_16x16x32_bf16 v[62:65], v[118:121], v[166:169], v[62:65]
	v_mfma_f32_16x16x32_bf16 v[46:49], v[110:113], v[170:173], v[46:49]
	v_mfma_f32_16x16x32_bf16 v[46:49], v[118:121], v[174:177], v[46:49]
	v_mfma_f32_16x16x32_bf16 v[30:33], v[110:113], v[178:181], v[30:33]
	v_mfma_f32_16x16x32_bf16 v[30:33], v[118:121], v[182:185], v[30:33]
	v_mfma_f32_16x16x32_bf16 v[14:17], v[110:113], v[186:189], v[14:17]
	v_mfma_f32_16x16x32_bf16 v[14:17], v[118:121], v[190:193], v[14:17]
	v_mfma_f32_16x16x32_bf16 v[58:61], v[138:141], v[162:165], v[58:61]
	v_mfma_f32_16x16x32_bf16 v[58:61], v[142:145], v[166:169], v[58:61]
	v_mfma_f32_16x16x32_bf16 v[42:45], v[138:141], v[170:173], v[42:45]
	v_mfma_f32_16x16x32_bf16 v[42:45], v[142:145], v[174:177], v[42:45]
	v_mfma_f32_16x16x32_bf16 v[26:29], v[138:141], v[178:181], v[26:29]
	v_mfma_f32_16x16x32_bf16 v[26:29], v[142:145], v[182:185], v[26:29]
	v_mfma_f32_16x16x32_bf16 v[10:13], v[138:141], v[186:189], v[10:13]
	v_mfma_f32_16x16x32_bf16 v[10:13], v[142:145], v[190:193], v[10:13]
	v_mfma_f32_16x16x32_bf16 v[54:57], v[146:149], v[162:165], v[54:57]
	v_mfma_f32_16x16x32_bf16 v[54:57], v[150:153], v[166:169], v[54:57]
	v_mfma_f32_16x16x32_bf16 v[38:41], v[146:149], v[170:173], v[38:41]
	v_mfma_f32_16x16x32_bf16 v[38:41], v[150:153], v[174:177], v[38:41]
	v_mfma_f32_16x16x32_bf16 v[22:25], v[146:149], v[178:181], v[22:25]
	v_mfma_f32_16x16x32_bf16 v[22:25], v[150:153], v[182:185], v[22:25]
	v_mfma_f32_16x16x32_bf16 v[6:9], v[146:149], v[186:189], v[6:9]
	v_mfma_f32_16x16x32_bf16 v[6:9], v[150:153], v[190:193], v[6:9]
	v_mfma_f32_16x16x32_bf16 v[50:53], v[154:157], v[162:165], v[50:53]
	v_mfma_f32_16x16x32_bf16 v[50:53], v[158:161], v[166:169], v[50:53]
	v_mfma_f32_16x16x32_bf16 v[34:37], v[154:157], v[170:173], v[34:37]
	v_mfma_f32_16x16x32_bf16 v[34:37], v[158:161], v[174:177], v[34:37]
	v_mfma_f32_16x16x32_bf16 v[18:21], v[154:157], v[178:181], v[18:21]
	v_mfma_f32_16x16x32_bf16 v[18:21], v[158:161], v[182:185], v[18:21]
	v_mfma_f32_16x16x32_bf16 v[2:5], v[154:157], v[186:189], v[2:5]
	v_mfma_f32_16x16x32_bf16 v[2:5], v[158:161], v[190:193], v[2:5]
	s_barrier
	s_setprio 0
	s_add_u32 s48, s48, 0x100
	s_addc_u32 s49, s49, 0
	s_add_u32 s50, s50, 0x100
	s_addc_u32 s51, s51, 0
	s_cmp_ge_u32 vcc_lo, s96
	s_mov_b32 s46, vcc_lo
	s_cbranch_scc0 .LBB0_274
	s_and_b64 vcc, exec, s[72:73]
	s_cbranch_vccz .LBB0_277
	s_barrier

; #define PG8_STAGE(bufoff, gbase, voff) do { _Pragma("unroll") for (int _i = 0; _i < 2; ++_i) \
;         __builtin_amdgcn_global_load_lds((const unsigned*)((const char*)(gbase) + (voff)[_i]), (PG8_LAS unsigned*)(lds + (bufoff) + ldsw + _i * 8192), 16, 0, 0); } while (0)
; #define PG8_LDA(dst, b, h) do { _Pragma("unroll") for (int m = 0; m < 4; ++m) _Pragma("unroll") for (int k = 0; k < 2; ++k) dst[m][k] = *(const PG8_LAS bf16x8*)(lds + PG8_SA(b, h) + aoff + m * 2048 + k * 1024); } while (0)
; #define PG8_LDB(dst, b, h) do { _Pragma("unroll") for (int n = 0; n < 2; ++n) _Pragma("unroll") for (int k = 0; k < 2; ++k) dst[n][k] = *(const PG8_LAS bf16x8*)(lds + PG8_SB(b, h) + boff + n * 2048 + k * 1024); } while (0)
; #define PG8_MMA(ai, bj, At, Bt) do { __builtin_amdgcn_s_setprio(1); _Pragma("unroll") for (int m = 0; m < 4; ++m) _Pragma("unroll") for (int n = 0; n < 2; ++n) _Pragma("unroll") for (int k = 0; k < 2; ++k) \
;         acc[ai][bj][m][n] = __builtin_amdgcn_mfma_f32_16x16x32_bf16(Bt[n][k], At[m][k], acc[ai][bj][m][n], 0, 0, 0); __builtin_amdgcn_s_setprio(0); } while (0)
; #define PG8_WAIT_V(n) asm volatile("s_waitcnt vmcnt(" #n ")" ::: "memory")
; #define PG8_WAIT_L(n) asm volatile("s_waitcnt lgkmcnt(" #n ")" ::: "memory")
; template <class Epi, class Sched, bool ALIGN_EPI = false, bool SP2 = false>
; __device__ __forceinline__ void gemm_phase(PG8_LAS unsigned char* lds, const Gemm g, const Sched& S, const Epi& E) {
;     ...
;             const bool last = (t == nt - 2);
;             const char* a1 = cA + (size_t)(t + 1) * kstep;
;             const char* a2 = last ? nA : cA + (size_t)(t + 2) * kstep; const char* b2 = last ? nB : cB + (size_t)(t + 2) * kstep;
;             const char* a3 = a2 + kstep; const char* b3 = b2 + kstep;
;             if (last && has_next) S.a_ready(nxt);
;             if constexpr (SP2) {
;             PG8_LDB(B0, 0, 0); PG8_LDB(B1, 0, 1); PG8_SCHED; PG8_LDA(At, 0, 0); PG8_STAGE(PG8_SA(1, 1), a1 + hstep, voffA);
;             PG8_WAIT_V(8); PG8_WAIT_L(0); PG8_BAR; PG8_MMA(0, 0, At, B0); PG8_MMA(0, 1, At, B1); PG8_BAR; PG8_SCHED;
;             PG8_LDA(At, 0, 1); PG8_STAGE(PG8_SB(0, 0), b2, voffB); PG8_STAGE(PG8_SB(0, 1), b2 + hstep, voffB); PG8_STAGE(PG8_SA(0, 0), a2, voffA);
;             PG8_WAIT_V(8); PG8_WAIT_L(0); PG8_BAR; PG8_MMA(1, 0, At, B0); PG8_MMA(1, 1, At, B1); PG8_BAR; PG8_SCHED;
.LBB0_408:
	s_add_u32 s38, s48, 0xfffc0080
	s_addc_u32 s39, s49, -1
	s_add_i32 s85, 0, 0x10000
	s_cmp_eq_u32 s84, 12
	s_cselect_b32 s73, s21, s39
	s_cselect_b32 s72, s27, s38
	v_add_u32_e32 v0, s85, v167
	s_cselect_b32 s47, s29, s69
	s_cselect_b32 s46, s33, s53
	s_add_i32 s38, 0, 0x14000
	ds_read_b128 v[142:145], v0
	ds_read_b128 v[146:149], v0 offset:1024
	ds_read_b128 v[150:153], v0 offset:2048
	ds_read_b128 v[154:157], v0 offset:3072
	v_add_u32_e32 v0, s38, v167
	ds_read_b128 v[158:161], v0
	ds_read_b128 v[162:165], v0 offset:1024
	ds_read_b128 v[172:175], v0 offset:2048
	ds_read_b128 v[176:179], v0 offset:3072
	v_lshl_add_u64 v[218:219], s[48:49], 0, v[138:139]
	s_add_i32 m0, s76, 0xc000
	ds_read_b128 v[180:183], v170
	ds_read_b128 v[184:187], v170 offset:1024
	ds_read_b128 v[188:191], v170 offset:2048
	ds_read_b128 v[192:195], v170 offset:3072
	ds_read_b128 v[202:205], v170 offset:4096
	ds_read_b128 v[206:209], v170 offset:5120
	ds_read_b128 v[210:213], v170 offset:6144
	ds_read_b128 v[214:217], v170 offset:7168
	global_load_lds_dwordx4 v[218:219], off
	v_lshl_add_u64 v[218:219], s[48:49], 0, v[140:141]
	s_add_i32 m0, s76, 0xe000
	s_nop 0
	global_load_lds_dwordx4 v[218:219], off
	s_waitcnt vmcnt(8)
	s_waitcnt lgkmcnt(0)
	s_barrier
	s_setprio 1
	v_mfma_f32_16x16x32_bf16 v[122:125], v[142:145], v[180:183], v[122:125]
	v_mfma_f32_16x16x32_bf16 v[122:125], v[146:149], v[184:187], v[122:125]
	v_mfma_f32_16x16x32_bf16 v[106:109], v[142:145], v[188:191], v[106:109]
	v_mfma_f32_16x16x32_bf16 v[106:109], v[146:149], v[192:195], v[106:109]
	v_mfma_f32_16x16x32_bf16 v[90:93], v[142:145], v[202:205], v[90:93]
	v_mfma_f32_16x16x32_bf16 v[90:93], v[146:149], v[206:209], v[90:93]
	v_mfma_f32_16x16x32_bf16 v[74:77], v[142:145], v[210:213], v[74:77]
	v_mfma_f32_16x16x32_bf16 v[74:77], v[146:149], v[214:217], v[74:77]
	v_mfma_f32_16x16x32_bf16 v[126:129], v[150:153], v[180:183], v[126:129]
	v_mfma_f32_16x16x32_bf16 v[126:129], v[154:157], v[184:187], v[126:129]
	v_mfma_f32_16x16x32_bf16 v[110:113], v[150:153], v[188:191], v[110:113]
	v_mfma_f32_16x16x32_bf16 v[110:113], v[154:157], v[192:195], v[110:113]
	v_mfma_f32_16x16x32_bf16 v[94:97], v[150:153], v[202:205], v[94:97]
	v_mfma_f32_16x16x32_bf16 v[94:97], v[154:157], v[206:209], v[94:97]
	v_mfma_f32_16x16x32_bf16 v[78:81], v[150:153], v[210:213], v[78:81]
	v_mfma_f32_16x16x32_bf16 v[78:81], v[154:157], v[214:217], v[78:81]
	v_mfma_f32_16x16x32_bf16 v[114:117], v[158:161], v[180:183], v[114:117]
	v_mfma_f32_16x16x32_bf16 v[114:117], v[162:165], v[184:187], v[114:117]
	v_mfma_f32_16x16x32_bf16 v[98:101], v[158:161], v[188:191], v[98:101]
	v_mfma_f32_16x16x32_bf16 v[98:101], v[162:165], v[192:195], v[98:101]
	v_mfma_f32_16x16x32_bf16 v[82:85], v[158:161], v[202:205], v[82:85]
	v_mfma_f32_16x16x32_bf16 v[82:85], v[162:165], v[206:209], v[82:85]
	v_mfma_f32_16x16x32_bf16 v[66:69], v[158:161], v[210:213], v[66:69]
	v_mfma_f32_16x16x32_bf16 v[66:69], v[162:165], v[214:217], v[66:69]
	v_mfma_f32_16x16x32_bf16 v[118:121], v[172:175], v[180:183], v[118:121]
	v_mfma_f32_16x16x32_bf16 v[118:121], v[176:179], v[184:187], v[118:121]
	v_mfma_f32_16x16x32_bf16 v[102:105], v[172:175], v[188:191], v[102:105]
	v_mfma_f32_16x16x32_bf16 v[102:105], v[176:179], v[192:195], v[102:105]
	v_mfma_f32_16x16x32_bf16 v[86:89], v[172:175], v[202:205], v[86:89]
	v_mfma_f32_16x16x32_bf16 v[86:89], v[176:179], v[206:209], v[86:89]
	v_mfma_f32_16x16x32_bf16 v[70:73], v[172:175], v[210:213], v[70:73]
	v_mfma_f32_16x16x32_bf16 v[70:73], v[176:179], v[214:217], v[70:73]
	s_barrier
	s_setprio 0
	s_add_i32 s39, s85, s75
	v_lshl_add_u64 v[218:219], s[46:47], 0, v[134:135]
	s_mov_b32 m0, s39
	ds_read_b128 v[180:183], v170 offset:16384
	ds_read_b128 v[184:187], v170 offset:17408
	ds_read_b128 v[188:191], v170 offset:18432
	ds_read_b128 v[192:195], v170 offset:19456
	ds_read_b128 v[202:205], v170 offset:20480
	ds_read_b128 v[206:209], v170 offset:21504
	ds_read_b128 v[210:213], v170 offset:22528
	ds_read_b128 v[214:217], v170 offset:23552
	global_load_lds_dwordx4 v[218:219], off
	s_add_i32 m0, s39, 0x2000
	s_add_u32 s92, s46, 0x40000
	v_lshl_add_u64 v[220:221], s[46:47], 0, v[130:131]
	s_addc_u32 s93, s47, 0
	s_add_i32 s38, s38, s75
	global_load_lds_dwordx4 v[220:221], off
	v_lshl_add_u64 v[222:223], s[92:93], 0, v[134:135]
	s_mov_b32 m0, s38
	v_lshl_add_u64 v[224:225], s[72:73], 0, v[132:133]
	global_load_lds_dwordx4 v[222:223], off
	v_lshl_add_u64 v[222:223], s[92:93], 0, v[130:131]
	s_add_i32 m0, s38, 0x2000
	s_nop 0
	global_load_lds_dwordx4 v[222:223], off
	v_lshl_add_u64 v[222:223], s[72:73], 0, v[136:137]
	s_mov_b32 m0, s76
	s_nop 0
	global_load_lds_dwordx4 v[222:223], off
	s_mov_b32 m0, s77
	s_nop 0
	global_load_lds_dwordx4 v[224:225], off
	s_waitcnt vmcnt(8)
	s_waitcnt lgkmcnt(0)
	s_barrier
; #define PG8_STAGE(bufoff, gbase, voff) do { _Pragma("unroll") for (int _i = 0; _i < 2; ++_i) \
;         __builtin_amdgcn_global_load_lds((const unsigned*)((const char*)(gbase) + (voff)[_i]), (PG8_LAS unsigned*)(lds + (bufoff) + ldsw + _i * 8192), 16, 0, 0); } while (0)
; #define PG8_LDA(dst, b, h) do { _Pragma("unroll") for (int m = 0; m < 4; ++m) _Pragma("unroll") for (int k = 0; k < 2; ++k) dst[m][k] = *(const PG8_LAS bf16x8*)(lds + PG8_SA(b, h) + aoff + m * 2048 + k * 1024); } while (0)
; #define PG8_LDB(dst, b, h) do { _Pragma("unroll") for (int n = 0; n < 2; ++n) _Pragma("unroll") for (int k = 0; k < 2; ++k) dst[n][k] = *(const PG8_LAS bf16x8*)(lds + PG8_SB(b, h) + boff + n * 2048 + k * 1024); } while (0)
; #define PG8_MMA(ai, bj, At, Bt) do { __builtin_amdgcn_s_setprio(1); _Pragma("unroll") for (int m = 0; m < 4; ++m) _Pragma("unroll") for (int n = 0; n < 2; ++n) _Pragma("unroll") for (int k = 0; k < 2; ++k) \
;         acc[ai][bj][m][n] = __builtin_amdgcn_mfma_f32_16x16x32_bf16(Bt[n][k], At[m][k], acc[ai][bj][m][n], 0, 0, 0); __builtin_amdgcn_s_setprio(0); } while (0)
; #define PG8_WAIT_V(n) asm volatile("s_waitcnt vmcnt(" #n ")" ::: "memory")
; #define PG8_WAIT_L(n) asm volatile("s_waitcnt lgkmcnt(" #n ")" ::: "memory")
; #define PG8_BAR __builtin_amdgcn_s_barrier()
; #define PG8_SCHED __builtin_amdgcn_sched_barrier(0)
; template <class Epi, class Sched, bool ALIGN_EPI = false, bool SP2 = false>
; __device__ __forceinline__ void gemm_phase(PG8_LAS unsigned char* lds, const Gemm g, const Sched& S, const Epi& E) {
;     ...
;             PG8_WAIT_V(8); PG8_WAIT_L(0); PG8_BAR; PG8_MMA(1, 0, At, B0); PG8_MMA(1, 1, At, B1); PG8_BAR; PG8_SCHED;
;             PG8_LDB(B0, 1, 0); PG8_LDB(B1, 1, 1); PG8_SCHED; PG8_LDA(At, 1, 0); PG8_STAGE(PG8_SA(0, 1), a2 + hstep, voffA);
;             PG8_WAIT_V(8); PG8_WAIT_L(0); PG8_BAR; PG8_MMA(0, 0, At, B0); PG8_MMA(0, 1, At, B1); PG8_BAR; PG8_SCHED;
	s_setprio 1
	v_mfma_f32_16x16x32_bf16 v[58:61], v[142:145], v[180:183], v[58:61]
	v_mfma_f32_16x16x32_bf16 v[58:61], v[146:149], v[184:187], v[58:61]
	v_mfma_f32_16x16x32_bf16 v[42:45], v[142:145], v[188:191], v[42:45]
	v_mfma_f32_16x16x32_bf16 v[42:45], v[146:149], v[192:195], v[42:45]
	v_mfma_f32_16x16x32_bf16 v[26:29], v[142:145], v[202:205], v[26:29]
	v_mfma_f32_16x16x32_bf16 v[26:29], v[146:149], v[206:209], v[26:29]
	v_mfma_f32_16x16x32_bf16 v[10:13], v[142:145], v[210:213], v[10:13]
	v_mfma_f32_16x16x32_bf16 v[10:13], v[146:149], v[214:217], v[10:13]
	v_mfma_f32_16x16x32_bf16 v[62:65], v[150:153], v[180:183], v[62:65]
	v_mfma_f32_16x16x32_bf16 v[62:65], v[154:157], v[184:187], v[62:65]
	v_mfma_f32_16x16x32_bf16 v[46:49], v[150:153], v[188:191], v[46:49]
	v_mfma_f32_16x16x32_bf16 v[46:49], v[154:157], v[192:195], v[46:49]
	v_mfma_f32_16x16x32_bf16 v[30:33], v[150:153], v[202:205], v[30:33]
	v_mfma_f32_16x16x32_bf16 v[30:33], v[154:157], v[206:209], v[30:33]
	v_mfma_f32_16x16x32_bf16 v[14:17], v[150:153], v[210:213], v[14:17]
	v_mfma_f32_16x16x32_bf16 v[14:17], v[154:157], v[214:217], v[14:17]
	v_mfma_f32_16x16x32_bf16 v[50:53], v[158:161], v[180:183], v[50:53]
	v_mfma_f32_16x16x32_bf16 v[50:53], v[162:165], v[184:187], v[50:53]
	v_mfma_f32_16x16x32_bf16 v[34:37], v[158:161], v[188:191], v[34:37]
	v_mfma_f32_16x16x32_bf16 v[34:37], v[162:165], v[192:195], v[34:37]
	v_mfma_f32_16x16x32_bf16 v[18:21], v[158:161], v[202:205], v[18:21]
	v_mfma_f32_16x16x32_bf16 v[18:21], v[162:165], v[206:209], v[18:21]
	v_mfma_f32_16x16x32_bf16 v[2:5], v[158:161], v[210:213], v[2:5]
	v_mfma_f32_16x16x32_bf16 v[2:5], v[162:165], v[214:217], v[2:5]
	v_mfma_f32_16x16x32_bf16 v[54:57], v[172:175], v[180:183], v[54:57]
	v_mfma_f32_16x16x32_bf16 v[54:57], v[176:179], v[184:187], v[54:57]
	v_mfma_f32_16x16x32_bf16 v[38:41], v[172:175], v[188:191], v[38:41]
	v_mfma_f32_16x16x32_bf16 v[38:41], v[176:179], v[192:195], v[38:41]
	v_mfma_f32_16x16x32_bf16 v[22:25], v[172:175], v[202:205], v[22:25]
	v_mfma_f32_16x16x32_bf16 v[22:25], v[176:179], v[206:209], v[22:25]
	v_mfma_f32_16x16x32_bf16 v[6:9], v[172:175], v[210:213], v[6:9]
	v_mfma_f32_16x16x32_bf16 v[6:9], v[176:179], v[214:217], v[6:9]
	s_barrier
	s_setprio 0
	s_add_i32 s38, 0, 0x18000
	v_add_u32_e32 v0, s38, v167
	s_add_i32 s39, 0, 0x1c000
	ds_read_b128 v[142:145], v0
	ds_read_b128 v[146:149], v0 offset:1024
	ds_read_b128 v[150:153], v0 offset:2048
	ds_read_b128 v[154:157], v0 offset:3072
	v_add_u32_e32 v0, s39, v167
	ds_read_b128 v[158:161], v0
	ds_read_b128 v[162:165], v0 offset:1024
	ds_read_b128 v[172:175], v0 offset:2048
	ds_read_b128 v[176:179], v0 offset:3072
	s_add_u32 s72, s72, 0x40000
	s_addc_u32 s73, s73, 0
	s_mov_b32 m0, s78
	v_lshl_add_u64 v[226:227], s[72:73], 0, v[136:137]
	ds_read_b128 v[180:183], v170 offset:32768
	ds_read_b128 v[184:187], v170 offset:33792
	ds_read_b128 v[188:191], v170 offset:34816
	ds_read_b128 v[192:195], v170 offset:35840
	ds_read_b128 v[202:205], v170 offset:36864
	ds_read_b128 v[206:209], v170 offset:37888
	ds_read_b128 v[210:213], v170 offset:38912
	ds_read_b128 v[214:217], v170 offset:39936
	global_load_lds_dwordx4 v[226:227], off
	v_lshl_add_u64 v[226:227], s[72:73], 0, v[132:133]
	s_mov_b32 m0, s79
	s_nop 0
	global_load_lds_dwordx4 v[226:227], off
	s_waitcnt vmcnt(8)
	s_waitcnt lgkmcnt(0)
	s_barrier
	s_setprio 1
	v_mfma_f32_16x16x32_bf16 v[122:125], v[142:145], v[180:183], v[122:125]
	v_mfma_f32_16x16x32_bf16 v[122:125], v[146:149], v[184:187], v[122:125]
	v_mfma_f32_16x16x32_bf16 v[106:109], v[142:145], v[188:191], v[106:109]
	v_mfma_f32_16x16x32_bf16 v[106:109], v[146:149], v[192:195], v[106:109]
	v_mfma_f32_16x16x32_bf16 v[90:93], v[142:145], v[202:205], v[90:93]
	v_mfma_f32_16x16x32_bf16 v[90:93], v[146:149], v[206:209], v[90:93]
	v_mfma_f32_16x16x32_bf16 v[74:77], v[142:145], v[210:213], v[74:77]
	v_mfma_f32_16x16x32_bf16 v[74:77], v[146:149], v[214:217], v[74:77]
	v_mfma_f32_16x16x32_bf16 v[126:129], v[150:153], v[180:183], v[126:129]
	v_mfma_f32_16x16x32_bf16 v[126:129], v[154:157], v[184:187], v[126:129]
	v_mfma_f32_16x16x32_bf16 v[110:113], v[150:153], v[188:191], v[110:113]
	v_mfma_f32_16x16x32_bf16 v[110:113], v[154:157], v[192:195], v[110:113]
	v_mfma_f32_16x16x32_bf16 v[94:97], v[150:153], v[202:205], v[94:97]
	v_mfma_f32_16x16x32_bf16 v[94:97], v[154:157], v[206:209], v[94:97]
	v_mfma_f32_16x16x32_bf16 v[78:81], v[150:153], v[210:213], v[78:81]
	v_mfma_f32_16x16x32_bf16 v[78:81], v[154:157], v[214:217], v[78:81]
	v_mfma_f32_16x16x32_bf16 v[114:117], v[158:161], v[180:183], v[114:117]
	v_mfma_f32_16x16x32_bf16 v[114:117], v[162:165], v[184:187], v[114:117]
	v_mfma_f32_16x16x32_bf16 v[98:101], v[158:161], v[188:191], v[98:101]
	v_mfma_f32_16x16x32_bf16 v[98:101], v[162:165], v[192:195], v[98:101]
	v_mfma_f32_16x16x32_bf16 v[82:85], v[158:161], v[202:205], v[82:85]
	v_mfma_f32_16x16x32_bf16 v[82:85], v[162:165], v[206:209], v[82:85]
	v_mfma_f32_16x16x32_bf16 v[66:69], v[158:161], v[210:213], v[66:69]
	v_mfma_f32_16x16x32_bf16 v[66:69], v[162:165], v[214:217], v[66:69]
	v_mfma_f32_16x16x32_bf16 v[118:121], v[172:175], v[180:183], v[118:121]
	v_mfma_f32_16x16x32_bf16 v[118:121], v[176:179], v[184:187], v[118:121]
	v_mfma_f32_16x16x32_bf16 v[102:105], v[172:175], v[188:191], v[102:105]
	v_mfma_f32_16x16x32_bf16 v[102:105], v[176:179], v[192:195], v[102:105]
	v_mfma_f32_16x16x32_bf16 v[86:89], v[172:175], v[202:205], v[86:89]
	v_mfma_f32_16x16x32_bf16 v[86:89], v[176:179], v[206:209], v[86:89]
	v_mfma_f32_16x16x32_bf16 v[70:73], v[172:175], v[210:213], v[70:73]
	v_mfma_f32_16x16x32_bf16 v[70:73], v[176:179], v[214:217], v[70:73]
	s_barrier
; #define PG8_STAGE(bufoff, gbase, voff) do { _Pragma("unroll") for (int _i = 0; _i < 2; ++_i) \
;         __builtin_amdgcn_global_load_lds((const unsigned*)((const char*)(gbase) + (voff)[_i]), (PG8_LAS unsigned*)(lds + (bufoff) + ldsw + _i * 8192), 16, 0, 0); } while (0)
; #define PG8_LDA(dst, b, h) do { _Pragma("unroll") for (int m = 0; m < 4; ++m) _Pragma("unroll") for (int k = 0; k < 2; ++k) dst[m][k] = *(const PG8_LAS bf16x8*)(lds + PG8_SA(b, h) + aoff + m * 2048 + k * 1024); } while (0)
; #define PG8_MMA(ai, bj, At, Bt) do { __builtin_amdgcn_s_setprio(1); _Pragma("unroll") for (int m = 0; m < 4; ++m) _Pragma("unroll") for (int n = 0; n < 2; ++n) _Pragma("unroll") for (int k = 0; k < 2; ++k) \
;         acc[ai][bj][m][n] = __builtin_amdgcn_mfma_f32_16x16x32_bf16(Bt[n][k], At[m][k], acc[ai][bj][m][n], 0, 0, 0); __builtin_amdgcn_s_setprio(0); } while (0)
; #define PG8_WAIT_V(n) asm volatile("s_waitcnt vmcnt(" #n ")" ::: "memory")
; #define PG8_WAIT_L(n) asm volatile("s_waitcnt lgkmcnt(" #n ")" ::: "memory")
; #define PG8_BAR __builtin_amdgcn_s_barrier()
; #define PG8_SCHED __builtin_amdgcn_sched_barrier(0)
; template <class Epi, class Sched, bool ALIGN_EPI = false, bool SP2 = false>
; __device__ __forceinline__ void gemm_phase(PG8_LAS unsigned char* lds, const Gemm g, const Sched& S, const Epi& E) {
;     ...
;             PG8_LDA(At, 1, 1); PG8_STAGE(PG8_SB(1, 0), b3, voffB); PG8_STAGE(PG8_SB(1, 1), b3 + hstep, voffB); PG8_STAGE(PG8_SA(1, 0), a3, voffA);
;             PG8_WAIT_V(8); PG8_WAIT_L(0); PG8_BAR; PG8_MMA(1, 0, At, B0); PG8_MMA(1, 1, At, B1); PG8_BAR; PG8_SCHED;
;     ...
;         if constexpr (ALIGN_EPI) { if (wr == 0) PG8_BAR; }
	s_setprio 0
	s_add_i32 s38, s38, s75
	v_lshl_add_u64 v[218:219], v[218:219], 0, s[30:31]
	s_mov_b32 m0, s38
	ds_read_b128 v[180:183], v170 offset:49152
	ds_read_b128 v[184:187], v170 offset:50176
	ds_read_b128 v[188:191], v170 offset:51200
	ds_read_b128 v[192:195], v170 offset:52224
	ds_read_b128 v[202:205], v170 offset:53248
	ds_read_b128 v[206:209], v170 offset:54272
	ds_read_b128 v[210:213], v170 offset:55296
	ds_read_b128 v[214:217], v170 offset:56320
	global_load_lds_dwordx4 v[218:219], off
	s_add_i32 m0, s38, 0x2000
	s_add_u32 s46, s46, 0x40080
	v_lshl_add_u64 v[218:219], v[220:221], 0, s[30:31]
	s_addc_u32 s47, s47, 0
	s_add_i32 s38, s39, s75
	global_load_lds_dwordx4 v[218:219], off
	v_lshl_add_u64 v[218:219], s[46:47], 0, v[134:135]
	s_mov_b32 m0, s38
	s_nop 0
	global_load_lds_dwordx4 v[218:219], off
	v_lshl_add_u64 v[218:219], s[46:47], 0, v[130:131]
	s_add_i32 m0, s38, 0x2000
	s_nop 0
	global_load_lds_dwordx4 v[218:219], off
	v_lshl_add_u64 v[218:219], v[222:223], 0, s[30:31]
	s_mov_b32 m0, s80
	s_nop 0
	global_load_lds_dwordx4 v[218:219], off
	v_lshl_add_u64 v[218:219], v[224:225], 0, s[30:31]
	s_mov_b32 m0, s81
	s_nop 0
	global_load_lds_dwordx4 v[218:219], off
	s_waitcnt vmcnt(8)
	s_waitcnt lgkmcnt(0)
	s_barrier
	s_setprio 1
	v_mfma_f32_16x16x32_bf16 v[58:61], v[142:145], v[180:183], v[58:61]
	v_mfma_f32_16x16x32_bf16 v[58:61], v[146:149], v[184:187], v[58:61]
	v_mfma_f32_16x16x32_bf16 v[42:45], v[142:145], v[188:191], v[42:45]
	v_mfma_f32_16x16x32_bf16 v[42:45], v[146:149], v[192:195], v[42:45]
	v_mfma_f32_16x16x32_bf16 v[26:29], v[142:145], v[202:205], v[26:29]
	v_mfma_f32_16x16x32_bf16 v[26:29], v[146:149], v[206:209], v[26:29]
	v_mfma_f32_16x16x32_bf16 v[10:13], v[142:145], v[210:213], v[10:13]
	v_mfma_f32_16x16x32_bf16 v[10:13], v[146:149], v[214:217], v[10:13]
	v_mfma_f32_16x16x32_bf16 v[62:65], v[150:153], v[180:183], v[62:65]
	v_mfma_f32_16x16x32_bf16 v[62:65], v[154:157], v[184:187], v[62:65]
	v_mfma_f32_16x16x32_bf16 v[46:49], v[150:153], v[188:191], v[46:49]
	v_mfma_f32_16x16x32_bf16 v[46:49], v[154:157], v[192:195], v[46:49]
	v_mfma_f32_16x16x32_bf16 v[30:33], v[150:153], v[202:205], v[30:33]
	v_mfma_f32_16x16x32_bf16 v[30:33], v[154:157], v[206:209], v[30:33]
	v_mfma_f32_16x16x32_bf16 v[14:17], v[150:153], v[210:213], v[14:17]
	v_mfma_f32_16x16x32_bf16 v[14:17], v[154:157], v[214:217], v[14:17]
	v_mfma_f32_16x16x32_bf16 v[50:53], v[158:161], v[180:183], v[50:53]
	v_mfma_f32_16x16x32_bf16 v[50:53], v[162:165], v[184:187], v[50:53]
	v_mfma_f32_16x16x32_bf16 v[34:37], v[158:161], v[188:191], v[34:37]
	v_mfma_f32_16x16x32_bf16 v[34:37], v[162:165], v[192:195], v[34:37]
	v_mfma_f32_16x16x32_bf16 v[18:21], v[158:161], v[202:205], v[18:21]
	v_mfma_f32_16x16x32_bf16 v[18:21], v[162:165], v[206:209], v[18:21]
	v_mfma_f32_16x16x32_bf16 v[2:5], v[158:161], v[210:213], v[2:5]
	v_mfma_f32_16x16x32_bf16 v[2:5], v[162:165], v[214:217], v[2:5]
	v_mfma_f32_16x16x32_bf16 v[54:57], v[172:175], v[180:183], v[54:57]
	v_mfma_f32_16x16x32_bf16 v[54:57], v[176:179], v[184:187], v[54:57]
	v_mfma_f32_16x16x32_bf16 v[38:41], v[172:175], v[188:191], v[38:41]
	v_mfma_f32_16x16x32_bf16 v[38:41], v[176:179], v[192:195], v[38:41]
	v_mfma_f32_16x16x32_bf16 v[22:25], v[172:175], v[202:205], v[22:25]
	v_mfma_f32_16x16x32_bf16 v[22:25], v[176:179], v[206:209], v[22:25]
	v_mfma_f32_16x16x32_bf16 v[6:9], v[172:175], v[210:213], v[6:9]
	v_mfma_f32_16x16x32_bf16 v[6:9], v[176:179], v[214:217], v[6:9]
	s_barrier
	s_setprio 0
	s_add_i32 s84, s84, 2
	s_add_u32 s48, s48, 0x100
	s_addc_u32 s49, s49, 0
	s_add_u32 s53, s53, 0x100
	s_addc_u32 s69, s69, 0
	s_cmp_gt_u32 s84, 13
	s_cbranch_scc0 .LBB0_408
	s_and_b64 vcc, exec, s[64:65]
	s_cbranch_vccz .LBB0_411
	s_barrier
